# in-proj epilogue: odd/even token-pair packing via cndmask+v_perm instead of exec-masked branches; sc1 on Y stores
# speedup vs baseline: 1.0160x; 1.0066x over previous
.LBB0_145:
	s_add_u32 s6, s2, 0xfffc0080
	s_addc_u32 s7, s3, -1
	s_add_i32 s29, 0, 0x10000
	v_add_u32_e32 v132, s29, v215
	ds_read_b128 v[128:131], v132
	ds_read_b128 v[158:161], v132 offset:1024
	ds_read_b128 v[162:165], v132 offset:2048
	ds_read_b128 v[166:169], v132 offset:3072
	s_cmp_eq_u32 s28, 12
	s_cselect_b32 s11, s9, s7
	s_cselect_b32 s10, s12, s6
	s_cselect_b32 s7, s13, s27
	s_cselect_b32 s6, s17, s19
	v_lshl_add_u64 v[190:191], s[2:3], 0, v[154:155]
	s_add_i32 m0, s50, 0xc000
	ds_read_b128 v[170:173], v216
	ds_read_b128 v[178:181], v216 offset:2048
	ds_read_b128 v[186:189], v216 offset:4096
	ds_read_b128 v[222:225], v216 offset:6144
	ds_read_b128 v[174:177], v216 offset:1024
	ds_read_b128 v[182:185], v216 offset:3072
	ds_read_b128 v[218:221], v216 offset:5120
	ds_read_b128 v[226:229], v216 offset:7168
	global_load_lds_dwordx4 v[190:191], off
	v_lshl_add_u64 v[190:191], s[2:3], 0, v[156:157]
	s_add_i32 m0, s50, 0xe000
	s_nop 0
	global_load_lds_dwordx4 v[190:191], off
	s_waitcnt lgkmcnt(8)
	s_barrier
	s_waitcnt lgkmcnt(4)
	s_setprio 1
	v_mfma_f32_16x16x32_bf16 v[124:127], v[128:131], v[170:173], v[124:127]
	v_mfma_f32_16x16x32_bf16 v[120:123], v[162:165], v[170:173], v[120:123]
	v_mfma_f32_16x16x32_bf16 v[108:111], v[128:131], v[178:181], v[108:111]
	v_mfma_f32_16x16x32_bf16 v[104:107], v[162:165], v[178:181], v[104:107]
	v_mfma_f32_16x16x32_bf16 v[92:95], v[128:131], v[186:189], v[92:95]
	v_mfma_f32_16x16x32_bf16 v[88:91], v[162:165], v[186:189], v[88:91]
	v_mfma_f32_16x16x32_bf16 v[76:79], v[128:131], v[222:225], v[76:79]
	v_mfma_f32_16x16x32_bf16 v[72:75], v[162:165], v[222:225], v[72:75]
	s_waitcnt lgkmcnt(0)
	v_mfma_f32_16x16x32_bf16 v[124:127], v[158:161], v[174:177], v[124:127]
	v_mfma_f32_16x16x32_bf16 v[120:123], v[166:169], v[174:177], v[120:123]
	v_mfma_f32_16x16x32_bf16 v[108:111], v[158:161], v[182:185], v[108:111]
	v_mfma_f32_16x16x32_bf16 v[104:107], v[166:169], v[182:185], v[104:107]
	v_mfma_f32_16x16x32_bf16 v[92:95], v[158:161], v[218:221], v[92:95]
	v_mfma_f32_16x16x32_bf16 v[88:91], v[166:169], v[218:221], v[88:91]
	v_mfma_f32_16x16x32_bf16 v[76:79], v[158:161], v[226:229], v[76:79]
	v_mfma_f32_16x16x32_bf16 v[72:75], v[166:169], v[226:229], v[72:75]
	s_setprio 0
	s_barrier
	s_add_i32 s34, 0, 0x14000
	s_add_i32 s29, s29, s15
	v_add_u32_e32 v132, s34, v215
	v_lshl_add_u64 v[190:191], s[6:7], 0, v[150:151]
	s_mov_b32 m0, s29
	ds_read_b128 v[230:233], v132
	ds_read_b128 v[238:241], v132 offset:2048
	ds_read_b128 v[234:237], v132 offset:1024
	ds_read_b128 v[242:245], v132 offset:3072
	global_load_lds_dwordx4 v[190:191], off
	v_lshl_add_u64 v[246:247], s[6:7], 0, v[152:153]
	s_add_i32 m0, s29, 0x2000
	s_nop 0
	global_load_lds_dwordx4 v[246:247], off
	s_barrier
	s_waitcnt lgkmcnt(2)
	s_setprio 1
	v_mfma_f32_16x16x32_bf16 v[116:119], v[230:233], v[170:173], v[116:119]
	v_mfma_f32_16x16x32_bf16 v[112:115], v[238:241], v[170:173], v[112:115]
	v_mfma_f32_16x16x32_bf16 v[100:103], v[230:233], v[178:181], v[100:103]
	v_mfma_f32_16x16x32_bf16 v[96:99], v[238:241], v[178:181], v[96:99]
	v_mfma_f32_16x16x32_bf16 v[84:87], v[230:233], v[186:189], v[84:87]
	v_mfma_f32_16x16x32_bf16 v[80:83], v[238:241], v[186:189], v[80:83]
	v_mfma_f32_16x16x32_bf16 v[68:71], v[230:233], v[222:225], v[68:71]
	v_mfma_f32_16x16x32_bf16 v[64:67], v[238:241], v[222:225], v[64:67]
	s_waitcnt lgkmcnt(0)
	v_mfma_f32_16x16x32_bf16 v[116:119], v[234:237], v[174:177], v[116:119]
	v_mfma_f32_16x16x32_bf16 v[112:115], v[242:245], v[174:177], v[112:115]
	v_mfma_f32_16x16x32_bf16 v[100:103], v[234:237], v[182:185], v[100:103]
	v_mfma_f32_16x16x32_bf16 v[96:99], v[242:245], v[182:185], v[96:99]
	v_mfma_f32_16x16x32_bf16 v[84:87], v[234:237], v[218:221], v[84:87]
	v_mfma_f32_16x16x32_bf16 v[80:83], v[242:245], v[218:221], v[80:83]
	v_mfma_f32_16x16x32_bf16 v[68:71], v[234:237], v[226:229], v[68:71]
	v_mfma_f32_16x16x32_bf16 v[64:67], v[242:245], v[226:229], v[64:67]
	s_setprio 0
	s_mov_b32 m0, s50
	v_lshl_add_u64 v[248:249], s[10:11], 0, v[150:151]
	s_barrier
	ds_read_b128 v[170:173], v216 offset:16384
	ds_read_b128 v[178:181], v216 offset:18432
	ds_read_b128 v[186:189], v216 offset:20480
	ds_read_b128 v[222:225], v216 offset:22528
	ds_read_b128 v[174:177], v216 offset:17408
	ds_read_b128 v[182:185], v216 offset:19456
	ds_read_b128 v[218:221], v216 offset:21504
	ds_read_b128 v[226:229], v216 offset:23552
	global_load_lds_dwordx4 v[248:249], off
	v_lshl_add_u64 v[250:251], s[10:11], 0, v[152:153]
	s_mov_b32 m0, s51
	s_nop 0
	global_load_lds_dwordx4 v[250:251], off
	s_barrier
	s_waitcnt lgkmcnt(4)
	s_setprio 1
	v_mfma_f32_16x16x32_bf16 v[60:63], v[128:131], v[170:173], v[60:63]
	v_mfma_f32_16x16x32_bf16 v[56:59], v[162:165], v[170:173], v[56:59]
	v_mfma_f32_16x16x32_bf16 v[44:47], v[128:131], v[178:181], v[44:47]
	v_mfma_f32_16x16x32_bf16 v[40:43], v[162:165], v[178:181], v[40:43]
	v_mfma_f32_16x16x32_bf16 v[28:31], v[128:131], v[186:189], v[28:31]
	v_mfma_f32_16x16x32_bf16 v[24:27], v[162:165], v[186:189], v[24:27]
	v_mfma_f32_16x16x32_bf16 v[12:15], v[128:131], v[222:225], v[12:15]
	v_mfma_f32_16x16x32_bf16 v[8:11], v[162:165], v[222:225], v[8:11]
	s_waitcnt lgkmcnt(0)
	v_mfma_f32_16x16x32_bf16 v[60:63], v[158:161], v[174:177], v[60:63]
	v_mfma_f32_16x16x32_bf16 v[56:59], v[166:169], v[174:177], v[56:59]
	v_mfma_f32_16x16x32_bf16 v[44:47], v[158:161], v[182:185], v[44:47]
	v_mfma_f32_16x16x32_bf16 v[40:43], v[166:169], v[182:185], v[40:43]
	v_mfma_f32_16x16x32_bf16 v[28:31], v[158:161], v[218:221], v[28:31]
	v_mfma_f32_16x16x32_bf16 v[24:27], v[166:169], v[218:221], v[24:27]
	v_mfma_f32_16x16x32_bf16 v[12:15], v[158:161], v[226:229], v[12:15]
	v_mfma_f32_16x16x32_bf16 v[8:11], v[166:169], v[226:229], v[8:11]
	s_setprio 0
	s_barrier
	s_add_u32 s30, s6, 0x40000
	s_addc_u32 s31, s7, 0
	s_add_i32 s29, s34, s15
	v_lshl_add_u64 v[128:129], s[30:31], 0, v[150:151]
	s_mov_b32 m0, s29
	s_nop 0
	global_load_lds_dwordx4 v[128:129], off
	v_lshl_add_u64 v[128:129], s[30:31], 0, v[152:153]
	s_add_i32 m0, s29, 0x2000
	s_nop 0
	global_load_lds_dwordx4 v[128:129], off
	s_waitcnt vmcnt(6)
	s_barrier
	s_setprio 1
	v_mfma_f32_16x16x32_bf16 v[52:55], v[230:233], v[170:173], v[52:55]
	v_mfma_f32_16x16x32_bf16 v[48:51], v[238:241], v[170:173], v[48:51]
	v_mfma_f32_16x16x32_bf16 v[36:39], v[230:233], v[178:181], v[36:39]
	v_mfma_f32_16x16x32_bf16 v[32:35], v[238:241], v[178:181], v[32:35]
	v_mfma_f32_16x16x32_bf16 v[20:23], v[230:233], v[186:189], v[20:23]
	v_mfma_f32_16x16x32_bf16 v[16:19], v[238:241], v[186:189], v[16:19]
	v_mfma_f32_16x16x32_bf16 v[4:7], v[230:233], v[222:225], v[4:7]
	v_mfma_f32_16x16x32_bf16 v[0:3], v[238:241], v[222:225], v[0:3]
	v_mfma_f32_16x16x32_bf16 v[52:55], v[234:237], v[174:177], v[52:55]
	v_mfma_f32_16x16x32_bf16 v[48:51], v[242:245], v[174:177], v[48:51]
	v_mfma_f32_16x16x32_bf16 v[36:39], v[234:237], v[182:185], v[36:39]
	v_mfma_f32_16x16x32_bf16 v[32:35], v[242:245], v[182:185], v[32:35]
	v_mfma_f32_16x16x32_bf16 v[20:23], v[234:237], v[218:221], v[20:23]
	v_mfma_f32_16x16x32_bf16 v[16:19], v[242:245], v[218:221], v[16:19]
	v_mfma_f32_16x16x32_bf16 v[4:7], v[234:237], v[226:229], v[4:7]
	v_mfma_f32_16x16x32_bf16 v[0:3], v[242:245], v[226:229], v[0:3]
	s_setprio 0
	s_add_i32 s29, 0, 0x18000
	v_add_u32_e32 v132, s29, v215
	s_barrier
	ds_read_b128 v[128:131], v132
	ds_read_b128 v[158:161], v132 offset:1024
	ds_read_b128 v[162:165], v132 offset:2048
	ds_read_b128 v[166:169], v132 offset:3072
	s_add_u32 s10, s10, 0x40000
	s_addc_u32 s11, s11, 0
	s_mov_b32 m0, s36
	v_lshl_add_u64 v[230:231], s[10:11], 0, v[150:151]
	ds_read_b128 v[170:173], v216 offset:32768
	ds_read_b128 v[178:181], v216 offset:34816
	ds_read_b128 v[186:189], v216 offset:36864
	ds_read_b128 v[222:225], v216 offset:38912
	ds_read_b128 v[174:177], v216 offset:33792
	ds_read_b128 v[182:185], v216 offset:35840
	ds_read_b128 v[218:221], v216 offset:37888
	ds_read_b128 v[226:229], v216 offset:39936
	global_load_lds_dwordx4 v[230:231], off
	v_lshl_add_u64 v[230:231], s[10:11], 0, v[152:153]
	s_mov_b32 m0, s37
	s_nop 0
	global_load_lds_dwordx4 v[230:231], off
	s_waitcnt lgkmcnt(8)
	s_barrier
	s_waitcnt lgkmcnt(4)
	s_setprio 1
	v_mfma_f32_16x16x32_bf16 v[124:127], v[128:131], v[170:173], v[124:127]
	v_mfma_f32_16x16x32_bf16 v[120:123], v[162:165], v[170:173], v[120:123]
	v_mfma_f32_16x16x32_bf16 v[108:111], v[128:131], v[178:181], v[108:111]
	v_mfma_f32_16x16x32_bf16 v[104:107], v[162:165], v[178:181], v[104:107]
	v_mfma_f32_16x16x32_bf16 v[92:95], v[128:131], v[186:189], v[92:95]
	v_mfma_f32_16x16x32_bf16 v[88:91], v[162:165], v[186:189], v[88:91]
	v_mfma_f32_16x16x32_bf16 v[76:79], v[128:131], v[222:225], v[76:79]
	v_mfma_f32_16x16x32_bf16 v[72:75], v[162:165], v[222:225], v[72:75]
	s_waitcnt lgkmcnt(0)
	v_mfma_f32_16x16x32_bf16 v[124:127], v[158:161], v[174:177], v[124:127]
	v_mfma_f32_16x16x32_bf16 v[120:123], v[166:169], v[174:177], v[120:123]
	v_mfma_f32_16x16x32_bf16 v[108:111], v[158:161], v[182:185], v[108:111]
	v_mfma_f32_16x16x32_bf16 v[104:107], v[166:169], v[182:185], v[104:107]
	v_mfma_f32_16x16x32_bf16 v[92:95], v[158:161], v[218:221], v[92:95]
	v_mfma_f32_16x16x32_bf16 v[88:91], v[166:169], v[218:221], v[88:91]
	v_mfma_f32_16x16x32_bf16 v[76:79], v[158:161], v[226:229], v[76:79]
	v_mfma_f32_16x16x32_bf16 v[72:75], v[166:169], v[226:229], v[72:75]
	s_setprio 0
	s_barrier
	s_add_i32 s10, 0, 0x1c000
	s_add_i32 s11, s29, s15
	v_add_u32_e32 v132, s10, v215
	v_lshl_add_u64 v[190:191], v[190:191], 0, s[66:67]
	s_mov_b32 m0, s11
	ds_read_b128 v[230:233], v132
	ds_read_b128 v[238:241], v132 offset:2048
	ds_read_b128 v[234:237], v132 offset:1024
	ds_read_b128 v[242:245], v132 offset:3072
	global_load_lds_dwordx4 v[190:191], off
	v_lshl_add_u64 v[190:191], v[246:247], 0, s[66:67]
	s_add_i32 m0, s11, 0x2000
	s_nop 0
	global_load_lds_dwordx4 v[190:191], off
	s_barrier
	s_waitcnt lgkmcnt(2)
	s_setprio 1
	v_mfma_f32_16x16x32_bf16 v[116:119], v[230:233], v[170:173], v[116:119]
	v_mfma_f32_16x16x32_bf16 v[112:115], v[238:241], v[170:173], v[112:115]
	v_mfma_f32_16x16x32_bf16 v[100:103], v[230:233], v[178:181], v[100:103]
	v_mfma_f32_16x16x32_bf16 v[96:99], v[238:241], v[178:181], v[96:99]
	v_mfma_f32_16x16x32_bf16 v[84:87], v[230:233], v[186:189], v[84:87]
	v_mfma_f32_16x16x32_bf16 v[80:83], v[238:241], v[186:189], v[80:83]
	v_mfma_f32_16x16x32_bf16 v[68:71], v[230:233], v[222:225], v[68:71]
	v_mfma_f32_16x16x32_bf16 v[64:67], v[238:241], v[222:225], v[64:67]
	s_waitcnt lgkmcnt(0)
	v_mfma_f32_16x16x32_bf16 v[116:119], v[234:237], v[174:177], v[116:119]
	v_mfma_f32_16x16x32_bf16 v[112:115], v[242:245], v[174:177], v[112:115]
	v_mfma_f32_16x16x32_bf16 v[100:103], v[234:237], v[182:185], v[100:103]
	v_mfma_f32_16x16x32_bf16 v[96:99], v[242:245], v[182:185], v[96:99]
	v_mfma_f32_16x16x32_bf16 v[84:87], v[234:237], v[218:221], v[84:87]
	v_mfma_f32_16x16x32_bf16 v[80:83], v[242:245], v[218:221], v[80:83]
	v_mfma_f32_16x16x32_bf16 v[68:71], v[234:237], v[226:229], v[68:71]
	v_mfma_f32_16x16x32_bf16 v[64:67], v[242:245], v[226:229], v[64:67]
	s_setprio 0
	s_mov_b32 m0, s52
	v_lshl_add_u64 v[190:191], v[248:249], 0, s[66:67]
	s_barrier
	ds_read_b128 v[170:173], v216 offset:49152
	ds_read_b128 v[178:181], v216 offset:51200
	ds_read_b128 v[186:189], v216 offset:53248
	ds_read_b128 v[222:225], v216 offset:55296
	ds_read_b128 v[174:177], v216 offset:50176
	ds_read_b128 v[182:185], v216 offset:52224
	ds_read_b128 v[218:221], v216 offset:54272
	ds_read_b128 v[226:229], v216 offset:56320
	global_load_lds_dwordx4 v[190:191], off
	v_lshl_add_u64 v[190:191], v[250:251], 0, s[66:67]
	s_mov_b32 m0, s53
	s_nop 0
	global_load_lds_dwordx4 v[190:191], off
	s_barrier
	s_waitcnt lgkmcnt(4)
	s_setprio 1
	v_mfma_f32_16x16x32_bf16 v[60:63], v[128:131], v[170:173], v[60:63]
	v_mfma_f32_16x16x32_bf16 v[56:59], v[162:165], v[170:173], v[56:59]
	v_mfma_f32_16x16x32_bf16 v[44:47], v[128:131], v[178:181], v[44:47]
	v_mfma_f32_16x16x32_bf16 v[40:43], v[162:165], v[178:181], v[40:43]
	v_mfma_f32_16x16x32_bf16 v[28:31], v[128:131], v[186:189], v[28:31]
	v_mfma_f32_16x16x32_bf16 v[24:27], v[162:165], v[186:189], v[24:27]
	v_mfma_f32_16x16x32_bf16 v[12:15], v[128:131], v[222:225], v[12:15]
	v_mfma_f32_16x16x32_bf16 v[8:11], v[162:165], v[222:225], v[8:11]
	s_waitcnt lgkmcnt(0)
	v_mfma_f32_16x16x32_bf16 v[60:63], v[158:161], v[174:177], v[60:63]
	v_mfma_f32_16x16x32_bf16 v[56:59], v[166:169], v[174:177], v[56:59]
	v_mfma_f32_16x16x32_bf16 v[44:47], v[158:161], v[182:185], v[44:47]
	v_mfma_f32_16x16x32_bf16 v[40:43], v[166:169], v[182:185], v[40:43]
	v_mfma_f32_16x16x32_bf16 v[28:31], v[158:161], v[218:221], v[28:31]
	v_mfma_f32_16x16x32_bf16 v[24:27], v[166:169], v[218:221], v[24:27]
	v_mfma_f32_16x16x32_bf16 v[12:15], v[158:161], v[226:229], v[12:15]
	v_mfma_f32_16x16x32_bf16 v[8:11], v[166:169], v[226:229], v[8:11]
	s_setprio 0
	s_barrier
	s_add_u32 s6, s6, 0x40080
	s_addc_u32 s7, s7, 0
	s_add_i32 s10, s10, s15
	v_lshl_add_u64 v[128:129], s[6:7], 0, v[150:151]
	s_mov_b32 m0, s10
	s_nop 0
	global_load_lds_dwordx4 v[128:129], off
	v_lshl_add_u64 v[128:129], s[6:7], 0, v[152:153]
	s_add_i32 m0, s10, 0x2000
	s_nop 0
	global_load_lds_dwordx4 v[128:129], off
	s_waitcnt vmcnt(6)
	s_barrier
	s_setprio 1
	v_mfma_f32_16x16x32_bf16 v[52:55], v[230:233], v[170:173], v[52:55]
	v_mfma_f32_16x16x32_bf16 v[48:51], v[238:241], v[170:173], v[48:51]
	v_mfma_f32_16x16x32_bf16 v[36:39], v[230:233], v[178:181], v[36:39]
	v_mfma_f32_16x16x32_bf16 v[32:35], v[238:241], v[178:181], v[32:35]
	v_mfma_f32_16x16x32_bf16 v[20:23], v[230:233], v[186:189], v[20:23]
	v_mfma_f32_16x16x32_bf16 v[16:19], v[238:241], v[186:189], v[16:19]
	v_mfma_f32_16x16x32_bf16 v[4:7], v[230:233], v[222:225], v[4:7]
	v_mfma_f32_16x16x32_bf16 v[0:3], v[238:241], v[222:225], v[0:3]
	v_mfma_f32_16x16x32_bf16 v[52:55], v[234:237], v[174:177], v[52:55]
	v_mfma_f32_16x16x32_bf16 v[48:51], v[242:245], v[174:177], v[48:51]
	v_mfma_f32_16x16x32_bf16 v[36:39], v[234:237], v[182:185], v[36:39]
	v_mfma_f32_16x16x32_bf16 v[32:35], v[242:245], v[182:185], v[32:35]
	v_mfma_f32_16x16x32_bf16 v[20:23], v[234:237], v[218:221], v[20:23]
	v_mfma_f32_16x16x32_bf16 v[16:19], v[242:245], v[218:221], v[16:19]
	v_mfma_f32_16x16x32_bf16 v[4:7], v[234:237], v[226:229], v[4:7]
	v_mfma_f32_16x16x32_bf16 v[0:3], v[242:245], v[226:229], v[0:3]
	s_setprio 0
	s_add_i32 s28, s28, 2
	s_add_u32 s2, s2, 0x100
	s_addc_u32 s3, s3, 0
	s_add_u32 s19, s19, 0x100
	s_addc_u32 s27, s27, 0
	s_cmp_gt_u32 s28, 13
	s_barrier
	s_cbranch_scc0 .LBB0_145
	v_mov_b32_e32 v166, v135
	s_mov_b64 s[2:3], s[0:1]
	v_readfirstlane_b32 s27, v166
	s_bfe_u32 s19, s27, 0x20006
	s_load_dwordx2 s[30:31], s[2:3], 0x88
	s_mov_b64 s[2:3], s[0:1]
	s_cmp_gt_i32 s8, 31
	s_load_dwordx2 s[28:29], s[2:3], 0x80
	s_cselect_b64 s[6:7], -1, 0
	s_cmp_lt_i32 s8, 32
	s_cselect_b64 s[2:3], -1, 0
	s_ashr_i32 s9, s27, 2
	s_lshl_b32 s8, s8, 8
	s_and_b32 s17, s9, 0xffffffc0
	v_and_b32_e32 v217, 15, v166
	s_add_i32 s17, s17, s8
	v_bfe_u32 v186, v166, 4, 2
	v_or_b32_e32 v158, s17, v217
	s_cmp_gt_i32 s26, 3
	s_mov_b64 s[8:9], -1
	s_cbranch_scc0 .LBB0_829
	s_cmp_gt_u32 s26, 5
	s_cbranch_scc0 .LBB0_409
	s_cmp_gt_u32 s26, 8
	s_cbranch_scc0 .LBB0_406
	v_and_b32_e32 v128, 1, v166
	v_cmp_eq_u32_e64 s[8:9], 0, v128
	v_cmp_eq_u32_e32 vcc, 1, v128
	v_cvt_pk_bf16_f32 v128, v124, v125
	v_cvt_pk_bf16_f32 v132, v126, v127
	s_nop 0
	v_cndmask_b32_e64 v129, v128, v132, s[8:9]
	s_nop 1
	v_mov_b32_dpp v129, v129 quad_perm:[1,0,3,2] row_mask:0xf bank_mask:0xf bound_ctrl:1
	s_mov_b32 s10, 0x05040100
	s_mov_b32 s11, 0x07060302
	v_cndmask_b32_e32 v128, v128, v129, vcc
	v_cndmask_b32_e32 v132, v129, v132, vcc
	v_perm_b32 v130, v132, v128, s10
	v_perm_b32 v131, v132, v128, s11
	s_add_i32 s58, s26, -9
	s_and_b64 s[10:11], s[6:7], exec
	s_movk_i32 s10, 0x100
	s_cselect_b32 s12, 0x800, s10
	s_lshl_b64 s[10:11], s[58:59], 22
	s_lshl_b32 s58, s12, 1
	v_lshlrev_b32_e32 v128, 2, v186
	s_add_i32 s12, s58, -1
	v_lshl_or_b32 v159, s19, 5, v128
	v_mov_b32_e32 v128, s12
	s_add_i32 s12, s17, 0xffffe000
	s_lshr_b32 s34, s17, 8
	s_ashr_i32 s35, s12, 11
	s_and_b64 s[12:13], s[6:7], exec
	s_cselect_b32 s12, s35, s34
	s_movk_i32 s13, 0x7ff
	s_cselect_b32 s34, s13, 0xff
	s_lshl_b32 s38, s12, 8
	s_and_b64 s[12:13], s[6:7], exec
	s_mov_b32 s12, 0xeea4400
	s_cselect_b32 s12, s12, 0xf6a4400
	s_cselect_b32 s35, 12, 9
	s_waitcnt lgkmcnt(0)
	s_add_u32 s12, s30, s12
	s_addc_u32 s13, s31, 0
	v_cndmask_b32_e64 v132, v128, 0, s[8:9]
	v_and_b32_e32 v160, s34, v158
	v_or_b32_e32 v128, s38, v159
	s_add_u32 s10, s12, s10
	v_ashrrev_i32_e32 v129, 31, v128
	s_addc_u32 s11, s13, s11
	v_lshlrev_b32_e32 v160, 1, v160
	v_mov_b32_e32 v161, v133
	v_lshl_add_u64 v[164:165], s[10:11], 0, v[160:161]
	v_lshlrev_b64 v[128:129], s35, v[128:129]
	v_lshl_add_u64 v[160:161], v[164:165], 0, v[128:129]
	v_lshl_add_u64 v[160:161], v[132:133], 1, v[160:161]
	global_store_dword v[160:161], v130, off
	v_lshl_add_u64 v[160:161], v[160:161], 0, s[58:59]
	global_store_dword v[160:161], v131, off
	v_cvt_pk_bf16_f32 v130, v120, v121
	v_cvt_pk_bf16_f32 v161, v122, v123
	s_nop 0
	v_cndmask_b32_e64 v131, v130, v161, s[8:9]
	s_nop 1
	v_mov_b32_dpp v131, v131 quad_perm:[1,0,3,2] row_mask:0xf bank_mask:0xf bound_ctrl:1
	s_mov_b32 s12, 0x05040100
	s_mov_b32 s13, 0x07060302
	v_cndmask_b32_e32 v130, v130, v131, vcc
	v_cndmask_b32_e32 v161, v131, v161, vcc
	v_perm_b32 v160, v161, v130, s12
	v_perm_b32 v162, v161, v130, s13
	v_or_b32_e32 v167, 16, v159
	v_or_b32_e32 v130, s38, v167
	v_ashrrev_i32_e32 v131, 31, v130
	v_lshlrev_b64 v[130:131], s35, v[130:131]
	v_lshl_add_u64 v[168:169], v[164:165], 0, v[130:131]
	v_lshl_add_u64 v[168:169], v[132:133], 1, v[168:169]
	global_store_dword v[168:169], v160, off
	v_lshl_add_u64 v[160:161], v[168:169], 0, s[58:59]
	global_store_dword v[160:161], v162, off
	v_cvt_pk_bf16_f32 v160, v116, v117
	v_cvt_pk_bf16_f32 v163, v118, v119
	s_nop 0
	v_cndmask_b32_e64 v161, v160, v163, s[8:9]
	s_nop 1
	v_mov_b32_dpp v161, v161 quad_perm:[1,0,3,2] row_mask:0xf bank_mask:0xf bound_ctrl:1
	s_mov_b32 s12, 0x05040100
	s_mov_b32 s13, 0x07060302
	v_cndmask_b32_e32 v160, v160, v161, vcc
	v_cndmask_b32_e32 v163, v161, v163, vcc
	v_perm_b32 v162, v163, v160, s12
	v_perm_b32 v169, v163, v160, s13
	v_or_b32_e32 v168, 0x80, v159
	v_or_b32_e32 v160, s38, v168
	v_ashrrev_i32_e32 v161, 31, v160
	v_lshlrev_b64 v[160:161], s35, v[160:161]
	v_lshl_add_u64 v[170:171], v[164:165], 0, v[160:161]
	v_lshl_add_u64 v[170:171], v[132:133], 1, v[170:171]
	global_store_dword v[170:171], v162, off
	v_lshl_add_u64 v[162:163], v[170:171], 0, s[58:59]
	global_store_dword v[162:163], v169, off
	v_cvt_pk_bf16_f32 v162, v112, v113
	v_cvt_pk_bf16_f32 v169, v114, v115
	s_nop 0
	v_cndmask_b32_e64 v163, v162, v169, s[8:9]
	s_nop 1
	v_mov_b32_dpp v163, v163 quad_perm:[1,0,3,2] row_mask:0xf bank_mask:0xf bound_ctrl:1
	s_mov_b32 s12, 0x05040100
	s_mov_b32 s13, 0x07060302
	v_cndmask_b32_e32 v162, v162, v163, vcc
	v_cndmask_b32_e32 v169, v163, v169, vcc
	v_perm_b32 v170, v169, v162, s12
	v_perm_b32 v171, v169, v162, s13
	v_or_b32_e32 v169, 0x90, v159
	v_or_b32_e32 v162, s38, v169
	v_ashrrev_i32_e32 v163, 31, v162
	v_lshlrev_b64 v[162:163], s35, v[162:163]
	v_lshl_add_u64 v[164:165], v[164:165], 0, v[162:163]
	v_lshl_add_u64 v[164:165], v[132:133], 1, v[164:165]
	global_store_dword v[164:165], v170, off
	v_lshl_add_u64 v[164:165], v[164:165], 0, s[58:59]
	global_store_dword v[164:165], v171, off
	v_cvt_pk_bf16_f32 v164, v108, v109
	v_cvt_pk_bf16_f32 v171, v110, v111
	s_nop 0
	v_cndmask_b32_e64 v165, v164, v171, s[8:9]
	s_nop 1
	v_mov_b32_dpp v165, v165 quad_perm:[1,0,3,2] row_mask:0xf bank_mask:0xf bound_ctrl:1
	s_mov_b32 s12, 0x05040100
	s_mov_b32 s13, 0x07060302
	v_cndmask_b32_e32 v164, v164, v165, vcc
	v_cndmask_b32_e32 v171, v165, v171, vcc
	v_perm_b32 v170, v171, v164, s12
	v_perm_b32 v172, v171, v164, s13
	v_bitop3_b32 v164, v158, s34, 16 bitop3:0xc8
	v_lshlrev_b32_e32 v164, 1, v164
	v_mov_b32_e32 v165, v133
	v_lshl_add_u64 v[164:165], s[10:11], 0, v[164:165]
	v_lshl_add_u64 v[174:175], v[164:165], 0, v[128:129]
	v_lshl_add_u64 v[174:175], v[132:133], 1, v[174:175]
	global_store_dword v[174:175], v170, off
	v_lshl_add_u64 v[170:171], v[174:175], 0, s[58:59]
	global_store_dword v[170:171], v172, off
	v_cvt_pk_bf16_f32 v171, v104, v105
	v_cvt_pk_bf16_f32 v173, v106, v107
	s_nop 0
	v_cndmask_b32_e64 v170, v171, v173, s[8:9]
	s_nop 1
	v_mov_b32_dpp v172, v170 quad_perm:[1,0,3,2] row_mask:0xf bank_mask:0xf bound_ctrl:1
	s_mov_b32 s12, 0x05040100
	s_mov_b32 s13, 0x07060302
	v_cndmask_b32_e32 v171, v171, v172, vcc
	v_cndmask_b32_e32 v173, v172, v173, vcc
	v_perm_b32 v170, v173, v171, s12
	v_perm_b32 v174, v173, v171, s13
	v_lshl_add_u64 v[172:173], v[164:165], 0, v[130:131]
	v_lshl_add_u64 v[172:173], v[132:133], 1, v[172:173]
	global_store_dword v[172:173], v170, off
	v_lshl_add_u64 v[170:171], v[172:173], 0, s[58:59]
	global_store_dword v[170:171], v174, off
	v_cvt_pk_bf16_f32 v171, v100, v101
	v_cvt_pk_bf16_f32 v173, v102, v103
	s_nop 0
	v_cndmask_b32_e64 v170, v171, v173, s[8:9]
	s_nop 1
	v_mov_b32_dpp v172, v170 quad_perm:[1,0,3,2] row_mask:0xf bank_mask:0xf bound_ctrl:1
	s_mov_b32 s12, 0x05040100
	s_mov_b32 s13, 0x07060302
	v_cndmask_b32_e32 v171, v171, v172, vcc
	v_cndmask_b32_e32 v173, v172, v173, vcc
	v_perm_b32 v170, v173, v171, s12
	v_perm_b32 v174, v173, v171, s13
	v_lshl_add_u64 v[172:173], v[164:165], 0, v[160:161]
	v_lshl_add_u64 v[172:173], v[132:133], 1, v[172:173]
	global_store_dword v[172:173], v170, off
	v_lshl_add_u64 v[170:171], v[172:173], 0, s[58:59]
	global_store_dword v[170:171], v174, off
	v_cvt_pk_bf16_f32 v171, v96, v97
	v_cvt_pk_bf16_f32 v173, v98, v99
	s_nop 0
	v_cndmask_b32_e64 v170, v171, v173, s[8:9]
	s_nop 1
	v_mov_b32_dpp v172, v170 quad_perm:[1,0,3,2] row_mask:0xf bank_mask:0xf bound_ctrl:1
	s_mov_b32 s12, 0x05040100
	s_mov_b32 s13, 0x07060302
	v_cndmask_b32_e32 v171, v171, v172, vcc
	v_cndmask_b32_e32 v173, v172, v173, vcc
	v_perm_b32 v170, v173, v171, s12
	v_perm_b32 v174, v173, v171, s13
	v_lshl_add_u64 v[164:165], v[164:165], 0, v[162:163]
	v_lshl_add_u64 v[164:165], v[132:133], 1, v[164:165]
	global_store_dword v[164:165], v170, off
	v_lshl_add_u64 v[164:165], v[164:165], 0, s[58:59]
	global_store_dword v[164:165], v174, off
	v_cvt_pk_bf16_f32 v164, v92, v93
	v_cvt_pk_bf16_f32 v171, v94, v95
	s_nop 0
	v_cndmask_b32_e64 v165, v164, v171, s[8:9]
	s_nop 1
	v_mov_b32_dpp v165, v165 quad_perm:[1,0,3,2] row_mask:0xf bank_mask:0xf bound_ctrl:1
	s_mov_b32 s12, 0x05040100
	s_mov_b32 s13, 0x07060302
	v_cndmask_b32_e32 v164, v164, v165, vcc
	v_cndmask_b32_e32 v171, v165, v171, vcc
	v_perm_b32 v170, v171, v164, s12
	v_perm_b32 v172, v171, v164, s13
	v_bitop3_b32 v164, v158, s34, 32 bitop3:0xc8
	v_lshlrev_b32_e32 v164, 1, v164
	v_mov_b32_e32 v165, v133
	v_lshl_add_u64 v[164:165], s[10:11], 0, v[164:165]
	v_lshl_add_u64 v[174:175], v[164:165], 0, v[128:129]
	v_lshl_add_u64 v[174:175], v[132:133], 1, v[174:175]
	global_store_dword v[174:175], v170, off
	v_lshl_add_u64 v[170:171], v[174:175], 0, s[58:59]
	global_store_dword v[170:171], v172, off
	v_cvt_pk_bf16_f32 v171, v88, v89
	v_cvt_pk_bf16_f32 v173, v90, v91
	s_nop 0
	v_cndmask_b32_e64 v170, v171, v173, s[8:9]
	s_nop 1
	v_mov_b32_dpp v172, v170 quad_perm:[1,0,3,2] row_mask:0xf bank_mask:0xf bound_ctrl:1
	s_mov_b32 s12, 0x05040100
	s_mov_b32 s13, 0x07060302
	v_cndmask_b32_e32 v171, v171, v172, vcc
	v_cndmask_b32_e32 v173, v172, v173, vcc
	v_perm_b32 v170, v173, v171, s12
	v_perm_b32 v174, v173, v171, s13
	v_lshl_add_u64 v[172:173], v[164:165], 0, v[130:131]
	v_lshl_add_u64 v[172:173], v[132:133], 1, v[172:173]
	global_store_dword v[172:173], v170, off
	v_lshl_add_u64 v[170:171], v[172:173], 0, s[58:59]
	global_store_dword v[170:171], v174, off
	v_cvt_pk_bf16_f32 v171, v84, v85
	v_cvt_pk_bf16_f32 v173, v86, v87
	s_nop 0
	v_cndmask_b32_e64 v170, v171, v173, s[8:9]
	s_nop 1
	v_mov_b32_dpp v172, v170 quad_perm:[1,0,3,2] row_mask:0xf bank_mask:0xf bound_ctrl:1
	s_mov_b32 s12, 0x05040100
	s_mov_b32 s13, 0x07060302
	v_cndmask_b32_e32 v171, v171, v172, vcc
	v_cndmask_b32_e32 v173, v172, v173, vcc
	v_perm_b32 v170, v173, v171, s12
	v_perm_b32 v174, v173, v171, s13
	v_lshl_add_u64 v[172:173], v[164:165], 0, v[160:161]
	v_lshl_add_u64 v[172:173], v[132:133], 1, v[172:173]
	global_store_dword v[172:173], v170, off
	v_lshl_add_u64 v[170:171], v[172:173], 0, s[58:59]
	global_store_dword v[170:171], v174, off
	v_cvt_pk_bf16_f32 v171, v80, v81
	v_cvt_pk_bf16_f32 v173, v82, v83
	s_nop 0
	v_cndmask_b32_e64 v170, v171, v173, s[8:9]
	s_nop 1
	v_mov_b32_dpp v172, v170 quad_perm:[1,0,3,2] row_mask:0xf bank_mask:0xf bound_ctrl:1
	s_mov_b32 s12, 0x05040100
	s_mov_b32 s13, 0x07060302
	v_cndmask_b32_e32 v171, v171, v172, vcc
	v_cndmask_b32_e32 v173, v172, v173, vcc
	v_perm_b32 v170, v173, v171, s12
	v_perm_b32 v174, v173, v171, s13
	v_lshl_add_u64 v[164:165], v[164:165], 0, v[162:163]
	v_lshl_add_u64 v[164:165], v[132:133], 1, v[164:165]
	global_store_dword v[164:165], v170, off
	v_lshl_add_u64 v[164:165], v[164:165], 0, s[58:59]
	global_store_dword v[164:165], v174, off
	v_cvt_pk_bf16_f32 v164, v76, v77
	v_cvt_pk_bf16_f32 v171, v78, v79
	s_nop 0
	v_cndmask_b32_e64 v165, v164, v171, s[8:9]
	s_nop 1
	v_mov_b32_dpp v165, v165 quad_perm:[1,0,3,2] row_mask:0xf bank_mask:0xf bound_ctrl:1
	s_mov_b32 s12, 0x05040100
	s_mov_b32 s13, 0x07060302
	v_cndmask_b32_e32 v164, v164, v165, vcc
	v_cndmask_b32_e32 v171, v165, v171, vcc
	v_perm_b32 v170, v171, v164, s12
	v_perm_b32 v172, v171, v164, s13
	v_bitop3_b32 v164, v158, s34, 48 bitop3:0xc8
	v_lshlrev_b32_e32 v164, 1, v164
	v_mov_b32_e32 v165, v133
	v_lshl_add_u64 v[164:165], s[10:11], 0, v[164:165]
	v_lshl_add_u64 v[128:129], v[164:165], 0, v[128:129]
	v_lshl_add_u64 v[128:129], v[132:133], 1, v[128:129]
	global_store_dword v[128:129], v170, off
	v_lshl_add_u64 v[128:129], v[128:129], 0, s[58:59]
	global_store_dword v[128:129], v172, off
	v_cvt_pk_bf16_f32 v129, v72, v73
	v_cvt_pk_bf16_f32 v171, v74, v75
	s_nop 0
	v_cndmask_b32_e64 v128, v129, v171, s[8:9]
	s_nop 1
	v_mov_b32_dpp v170, v128 quad_perm:[1,0,3,2] row_mask:0xf bank_mask:0xf bound_ctrl:1
	s_mov_b32 s12, 0x05040100
	s_mov_b32 s13, 0x07060302
	v_cndmask_b32_e32 v129, v129, v170, vcc
	v_cndmask_b32_e32 v171, v170, v171, vcc
	v_perm_b32 v128, v171, v129, s12
	v_perm_b32 v172, v171, v129, s13
	v_lshl_add_u64 v[130:131], v[164:165], 0, v[130:131]
	v_lshl_add_u64 v[130:131], v[132:133], 1, v[130:131]
	global_store_dword v[130:131], v128, off
	v_lshl_add_u64 v[128:129], v[130:131], 0, s[58:59]
	global_store_dword v[128:129], v172, off
	v_cvt_pk_bf16_f32 v129, v68, v69
	v_cvt_pk_bf16_f32 v131, v70, v71
	s_nop 0
	v_cndmask_b32_e64 v128, v129, v131, s[8:9]
	s_nop 1
	v_mov_b32_dpp v130, v128 quad_perm:[1,0,3,2] row_mask:0xf bank_mask:0xf bound_ctrl:1
	s_mov_b32 s12, 0x05040100
	s_mov_b32 s13, 0x07060302
	v_cndmask_b32_e32 v129, v129, v130, vcc
	v_cndmask_b32_e32 v131, v130, v131, vcc
	v_perm_b32 v128, v131, v129, s12
	v_perm_b32 v170, v131, v129, s13
	v_lshl_add_u64 v[130:131], v[164:165], 0, v[160:161]
	v_lshl_add_u64 v[130:131], v[132:133], 1, v[130:131]
	global_store_dword v[130:131], v128, off
	v_lshl_add_u64 v[128:129], v[130:131], 0, s[58:59]
	global_store_dword v[128:129], v170, off
	v_cvt_pk_bf16_f32 v129, v64, v65
	v_cvt_pk_bf16_f32 v131, v66, v67
	s_nop 0
	v_cndmask_b32_e64 v128, v129, v131, s[8:9]
	s_nop 1
	v_mov_b32_dpp v130, v128 quad_perm:[1,0,3,2] row_mask:0xf bank_mask:0xf bound_ctrl:1
	s_mov_b32 s12, 0x05040100
	s_mov_b32 s13, 0x07060302
	v_cndmask_b32_e32 v129, v129, v130, vcc
	v_cndmask_b32_e32 v131, v130, v131, vcc
	v_perm_b32 v128, v131, v129, s12
	v_perm_b32 v160, v131, v129, s13
	v_lshl_add_u64 v[130:131], v[164:165], 0, v[162:163]
	v_lshl_add_u64 v[130:131], v[132:133], 1, v[130:131]
	global_store_dword v[130:131], v128, off
	v_lshl_add_u64 v[128:129], v[130:131], 0, s[58:59]
	global_store_dword v[128:129], v160, off
	v_cvt_pk_bf16_f32 v128, v60, v61
	v_cvt_pk_bf16_f32 v160, v62, v63
	s_nop 0
	v_cndmask_b32_e64 v129, v128, v160, s[8:9]
	s_nop 1
	v_mov_b32_dpp v129, v129 quad_perm:[1,0,3,2] row_mask:0xf bank_mask:0xf bound_ctrl:1
	s_mov_b32 s12, 0x05040100
	s_mov_b32 s13, 0x07060302
	v_cndmask_b32_e32 v128, v128, v129, vcc
	v_cndmask_b32_e32 v160, v129, v160, vcc
	v_perm_b32 v130, v160, v128, s12
	v_perm_b32 v131, v160, v128, s13
	s_add_i32 s12, s17, 0xffffe080
	v_add_u32_e32 v128, 0x80, v158
	s_ashr_i32 s12, s12, 11
	v_lshrrev_b32_e32 v129, 8, v128
	v_mov_b32_e32 v160, s12
	v_cndmask_b32_e64 v129, v129, v160, s[6:7]
	v_lshlrev_b32_e32 v162, 8, v129
	v_and_b32_e32 v160, s34, v128
	v_or_b32_e32 v128, v162, v159
	v_ashrrev_i32_e32 v129, 31, v128
	v_lshlrev_b32_e32 v160, 1, v160
	v_mov_b32_e32 v161, v133
	v_lshl_add_u64 v[164:165], s[10:11], 0, v[160:161]
	v_lshlrev_b64 v[128:129], s35, v[128:129]
	v_lshl_add_u64 v[160:161], v[164:165], 0, v[128:129]
	v_lshl_add_u64 v[160:161], v[132:133], 1, v[160:161]
	global_store_dword v[160:161], v130, off
	v_lshl_add_u64 v[160:161], v[160:161], 0, s[58:59]
	global_store_dword v[160:161], v131, off
	v_cvt_pk_bf16_f32 v130, v56, v57
	v_cvt_pk_bf16_f32 v160, v58, v59
	s_nop 0
	v_cndmask_b32_e64 v131, v130, v160, s[8:9]
	s_nop 1
	v_mov_b32_dpp v131, v131 quad_perm:[1,0,3,2] row_mask:0xf bank_mask:0xf bound_ctrl:1
	s_mov_b32 s12, 0x05040100
	s_mov_b32 s13, 0x07060302
	v_cndmask_b32_e32 v130, v130, v131, vcc
	v_cndmask_b32_e32 v160, v131, v160, vcc
	v_perm_b32 v159, v160, v130, s12
	v_perm_b32 v161, v160, v130, s13
	v_or_b32_e32 v130, v162, v167
	v_ashrrev_i32_e32 v131, 31, v130
	v_lshlrev_b64 v[130:131], s35, v[130:131]
	v_lshl_add_u64 v[170:171], v[164:165], 0, v[130:131]
	v_lshl_add_u64 v[170:171], v[132:133], 1, v[170:171]
	global_store_dword v[170:171], v159, off
	v_lshl_add_u64 v[170:171], v[170:171], 0, s[58:59]
	v_cvt_pk_bf16_f32 v160, v52, v53
	v_cvt_pk_bf16_f32 v163, v54, v55
	global_store_dword v[170:171], v161, off
	v_cndmask_b32_e64 v159, v160, v163, s[8:9]
	s_nop 1
	v_mov_b32_dpp v161, v159 quad_perm:[1,0,3,2] row_mask:0xf bank_mask:0xf bound_ctrl:1
	s_mov_b32 s12, 0x05040100
	s_mov_b32 s13, 0x07060302
	v_cndmask_b32_e32 v160, v160, v161, vcc
	v_cndmask_b32_e32 v163, v161, v163, vcc
	v_perm_b32 v159, v163, v160, s12
	v_perm_b32 v167, v163, v160, s13
	v_or_b32_e32 v160, v162, v168
	v_ashrrev_i32_e32 v161, 31, v160
	v_lshlrev_b64 v[160:161], s35, v[160:161]
	v_lshl_add_u64 v[170:171], v[164:165], 0, v[160:161]
	v_lshl_add_u64 v[170:171], v[132:133], 1, v[170:171]
	global_store_dword v[170:171], v159, off
	v_lshl_add_u64 v[170:171], v[170:171], 0, s[58:59]
	v_cvt_pk_bf16_f32 v163, v48, v49
	v_cvt_pk_bf16_f32 v168, v50, v51
	global_store_dword v[170:171], v167, off
	v_cndmask_b32_e64 v159, v163, v168, s[8:9]
	s_nop 1
	v_mov_b32_dpp v167, v159 quad_perm:[1,0,3,2] row_mask:0xf bank_mask:0xf bound_ctrl:1
	s_mov_b32 s12, 0x05040100
	s_mov_b32 s13, 0x07060302
	v_cndmask_b32_e32 v163, v163, v167, vcc
	v_cndmask_b32_e32 v168, v167, v168, vcc
	v_perm_b32 v159, v168, v163, s12
	v_perm_b32 v170, v168, v163, s13
	v_or_b32_e32 v162, v162, v169
	v_ashrrev_i32_e32 v163, 31, v162
	v_lshlrev_b64 v[162:163], s35, v[162:163]
	v_lshl_add_u64 v[164:165], v[164:165], 0, v[162:163]
	v_lshl_add_u64 v[164:165], v[132:133], 1, v[164:165]
	global_store_dword v[164:165], v159, off
	v_lshl_add_u64 v[164:165], v[164:165], 0, s[58:59]
	global_store_dword v[164:165], v170, off
	v_cvt_pk_bf16_f32 v164, v44, v45
	v_cvt_pk_bf16_f32 v167, v46, v47
	s_nop 0
	v_cndmask_b32_e64 v159, v164, v167, s[8:9]
	s_nop 1
	v_mov_b32_dpp v165, v159 quad_perm:[1,0,3,2] row_mask:0xf bank_mask:0xf bound_ctrl:1
	s_mov_b32 s12, 0x05040100
	s_mov_b32 s13, 0x07060302
	v_cndmask_b32_e32 v164, v164, v165, vcc
	v_cndmask_b32_e32 v167, v165, v167, vcc
	v_perm_b32 v159, v167, v164, s12
	v_perm_b32 v168, v167, v164, s13
	v_add_u32_e32 v164, 0x90, v158
	v_and_b32_e32 v164, s34, v164
	v_lshlrev_b32_e32 v164, 1, v164
	v_mov_b32_e32 v165, v133
	v_lshl_add_u64 v[164:165], s[10:11], 0, v[164:165]
	v_lshl_add_u64 v[170:171], v[164:165], 0, v[128:129]
	v_lshl_add_u64 v[170:171], v[132:133], 1, v[170:171]
	global_store_dword v[170:171], v159, off
	v_lshl_add_u64 v[170:171], v[170:171], 0, s[58:59]
	v_cvt_pk_bf16_f32 v167, v40, v41
	v_cvt_pk_bf16_f32 v169, v42, v43
	global_store_dword v[170:171], v168, off
	v_cndmask_b32_e64 v159, v167, v169, s[8:9]
	s_nop 1
	v_mov_b32_dpp v168, v159 quad_perm:[1,0,3,2] row_mask:0xf bank_mask:0xf bound_ctrl:1
	s_mov_b32 s12, 0x05040100
	s_mov_b32 s13, 0x07060302
	v_cndmask_b32_e32 v167, v167, v168, vcc
	v_cndmask_b32_e32 v169, v168, v169, vcc
	v_perm_b32 v159, v169, v167, s12
	v_perm_b32 v170, v169, v167, s13
	v_lshl_add_u64 v[168:169], v[164:165], 0, v[130:131]
	v_lshl_add_u64 v[168:169], v[132:133], 1, v[168:169]
	global_store_dword v[168:169], v159, off
	v_lshl_add_u64 v[168:169], v[168:169], 0, s[58:59]
	global_store_dword v[168:169], v170, off
	v_cvt_pk_bf16_f32 v167, v36, v37
	v_cvt_pk_bf16_f32 v169, v38, v39
	s_nop 0
	v_cndmask_b32_e64 v159, v167, v169, s[8:9]
	s_nop 1
	v_mov_b32_dpp v168, v159 quad_perm:[1,0,3,2] row_mask:0xf bank_mask:0xf bound_ctrl:1
	s_mov_b32 s12, 0x05040100
	s_mov_b32 s13, 0x07060302
	v_cndmask_b32_e32 v167, v167, v168, vcc
	v_cndmask_b32_e32 v169, v168, v169, vcc
	v_perm_b32 v159, v169, v167, s12
	v_perm_b32 v170, v169, v167, s13
	v_lshl_add_u64 v[168:169], v[164:165], 0, v[160:161]
	v_lshl_add_u64 v[168:169], v[132:133], 1, v[168:169]
	global_store_dword v[168:169], v159, off
	v_lshl_add_u64 v[168:169], v[168:169], 0, s[58:59]
	global_store_dword v[168:169], v170, off
	v_cvt_pk_bf16_f32 v167, v32, v33
	v_cvt_pk_bf16_f32 v169, v34, v35
	s_nop 0
	v_cndmask_b32_e64 v159, v167, v169, s[8:9]
	s_nop 1
	v_mov_b32_dpp v168, v159 quad_perm:[1,0,3,2] row_mask:0xf bank_mask:0xf bound_ctrl:1
	s_mov_b32 s12, 0x05040100
	s_mov_b32 s13, 0x07060302
	v_cndmask_b32_e32 v167, v167, v168, vcc
	v_cndmask_b32_e32 v169, v168, v169, vcc
	v_perm_b32 v159, v169, v167, s12
	v_perm_b32 v170, v169, v167, s13
	v_lshl_add_u64 v[164:165], v[164:165], 0, v[162:163]
	v_lshl_add_u64 v[164:165], v[132:133], 1, v[164:165]
	global_store_dword v[164:165], v159, off
	v_lshl_add_u64 v[164:165], v[164:165], 0, s[58:59]
	global_store_dword v[164:165], v170, off
	v_cvt_pk_bf16_f32 v164, v28, v29
	v_cvt_pk_bf16_f32 v167, v30, v31
	s_nop 0
	v_cndmask_b32_e64 v159, v164, v167, s[8:9]
	s_nop 1
	v_mov_b32_dpp v165, v159 quad_perm:[1,0,3,2] row_mask:0xf bank_mask:0xf bound_ctrl:1
	s_mov_b32 s12, 0x05040100
	s_mov_b32 s13, 0x07060302
	v_cndmask_b32_e32 v164, v164, v165, vcc
	v_cndmask_b32_e32 v167, v165, v167, vcc
	v_perm_b32 v159, v167, v164, s12
	v_perm_b32 v168, v167, v164, s13
	v_add_u32_e32 v164, 0xa0, v158
	v_and_b32_e32 v164, s34, v164
	v_lshlrev_b32_e32 v164, 1, v164
	v_mov_b32_e32 v165, v133
	v_lshl_add_u64 v[164:165], s[10:11], 0, v[164:165]
	v_lshl_add_u64 v[170:171], v[164:165], 0, v[128:129]
	v_lshl_add_u64 v[170:171], v[132:133], 1, v[170:171]
	global_store_dword v[170:171], v159, off
	v_lshl_add_u64 v[170:171], v[170:171], 0, s[58:59]
	v_cvt_pk_bf16_f32 v167, v24, v25
	v_cvt_pk_bf16_f32 v169, v26, v27
	global_store_dword v[170:171], v168, off
	v_cndmask_b32_e64 v159, v167, v169, s[8:9]
	s_nop 1
	v_mov_b32_dpp v168, v159 quad_perm:[1,0,3,2] row_mask:0xf bank_mask:0xf bound_ctrl:1
	s_mov_b32 s12, 0x05040100
	s_mov_b32 s13, 0x07060302
	v_cndmask_b32_e32 v167, v167, v168, vcc
	v_cndmask_b32_e32 v169, v168, v169, vcc
	v_perm_b32 v159, v169, v167, s12
	v_perm_b32 v170, v169, v167, s13
	v_lshl_add_u64 v[168:169], v[164:165], 0, v[130:131]
	v_lshl_add_u64 v[168:169], v[132:133], 1, v[168:169]
	global_store_dword v[168:169], v159, off
	v_lshl_add_u64 v[168:169], v[168:169], 0, s[58:59]
	global_store_dword v[168:169], v170, off
	v_cvt_pk_bf16_f32 v167, v20, v21
	v_cvt_pk_bf16_f32 v169, v22, v23
	s_nop 0
	v_cndmask_b32_e64 v159, v167, v169, s[8:9]
	s_nop 1
	v_mov_b32_dpp v168, v159 quad_perm:[1,0,3,2] row_mask:0xf bank_mask:0xf bound_ctrl:1
	s_mov_b32 s12, 0x05040100
	s_mov_b32 s13, 0x07060302
	v_cndmask_b32_e32 v167, v167, v168, vcc
	v_cndmask_b32_e32 v169, v168, v169, vcc
	v_perm_b32 v159, v169, v167, s12
	v_perm_b32 v170, v169, v167, s13
	v_lshl_add_u64 v[168:169], v[164:165], 0, v[160:161]
	v_lshl_add_u64 v[168:169], v[132:133], 1, v[168:169]
	global_store_dword v[168:169], v159, off
	v_lshl_add_u64 v[168:169], v[168:169], 0, s[58:59]
	global_store_dword v[168:169], v170, off
	v_cvt_pk_bf16_f32 v167, v16, v17
	v_cvt_pk_bf16_f32 v169, v18, v19
	s_nop 0
	v_cndmask_b32_e64 v159, v167, v169, s[8:9]
	s_nop 1
	v_mov_b32_dpp v168, v159 quad_perm:[1,0,3,2] row_mask:0xf bank_mask:0xf bound_ctrl:1
	s_mov_b32 s12, 0x05040100
	s_mov_b32 s13, 0x07060302
	v_cndmask_b32_e32 v167, v167, v168, vcc
	v_cndmask_b32_e32 v169, v168, v169, vcc
	v_perm_b32 v159, v169, v167, s12
	v_perm_b32 v170, v169, v167, s13
	v_lshl_add_u64 v[164:165], v[164:165], 0, v[162:163]
	v_lshl_add_u64 v[164:165], v[132:133], 1, v[164:165]
	global_store_dword v[164:165], v159, off
	v_lshl_add_u64 v[164:165], v[164:165], 0, s[58:59]
	global_store_dword v[164:165], v170, off
	v_cvt_pk_bf16_f32 v164, v12, v13
	v_cvt_pk_bf16_f32 v167, v14, v15
	s_nop 0
	v_cndmask_b32_e64 v159, v164, v167, s[8:9]
	s_nop 1
	v_mov_b32_dpp v165, v159 quad_perm:[1,0,3,2] row_mask:0xf bank_mask:0xf bound_ctrl:1
	s_mov_b32 s12, 0x05040100
	s_mov_b32 s13, 0x07060302
	v_cndmask_b32_e32 v164, v164, v165, vcc
	v_cndmask_b32_e32 v167, v165, v167, vcc
	v_perm_b32 v159, v167, v164, s12
	v_perm_b32 v168, v167, v164, s13
	v_add_u32_e32 v164, 0xb0, v158
	v_and_b32_e32 v164, s34, v164
	v_lshlrev_b32_e32 v164, 1, v164
	v_mov_b32_e32 v165, v133
	v_lshl_add_u64 v[164:165], s[10:11], 0, v[164:165]
	v_lshl_add_u64 v[128:129], v[164:165], 0, v[128:129]
	v_lshl_add_u64 v[128:129], v[132:133], 1, v[128:129]
	global_store_dword v[128:129], v159, off
	v_lshl_add_u64 v[128:129], v[128:129], 0, s[58:59]
	global_store_dword v[128:129], v168, off
	v_cvt_pk_bf16_f32 v129, v8, v9
	v_cvt_pk_bf16_f32 v167, v10, v11
	s_nop 0
	v_cndmask_b32_e64 v128, v129, v167, s[8:9]
	s_nop 1
	v_mov_b32_dpp v159, v128 quad_perm:[1,0,3,2] row_mask:0xf bank_mask:0xf bound_ctrl:1
	s_mov_b32 s10, 0x05040100
	s_mov_b32 s11, 0x07060302
	v_cndmask_b32_e32 v129, v129, v159, vcc
	v_cndmask_b32_e32 v167, v159, v167, vcc
	v_perm_b32 v128, v167, v129, s10
	v_perm_b32 v168, v167, v129, s11
	v_lshl_add_u64 v[130:131], v[164:165], 0, v[130:131]
	v_lshl_add_u64 v[130:131], v[132:133], 1, v[130:131]
	global_store_dword v[130:131], v128, off
	v_lshl_add_u64 v[128:129], v[130:131], 0, s[58:59]
	global_store_dword v[128:129], v168, off
	v_cvt_pk_bf16_f32 v129, v4, v5
	v_cvt_pk_bf16_f32 v131, v6, v7
	s_nop 0
	v_cndmask_b32_e64 v128, v129, v131, s[8:9]
	s_nop 1
	v_mov_b32_dpp v130, v128 quad_perm:[1,0,3,2] row_mask:0xf bank_mask:0xf bound_ctrl:1
	s_mov_b32 s10, 0x05040100
	s_mov_b32 s11, 0x07060302
	v_cndmask_b32_e32 v129, v129, v130, vcc
	v_cndmask_b32_e32 v131, v130, v131, vcc
	v_perm_b32 v128, v131, v129, s10
	v_perm_b32 v159, v131, v129, s11
	v_lshl_add_u64 v[130:131], v[164:165], 0, v[160:161]
	v_lshl_add_u64 v[130:131], v[132:133], 1, v[130:131]
	global_store_dword v[130:131], v128, off
	v_lshl_add_u64 v[128:129], v[130:131], 0, s[58:59]
	global_store_dword v[128:129], v159, off
	v_cvt_pk_bf16_f32 v129, v0, v1
	v_cvt_pk_bf16_f32 v131, v2, v3
	s_nop 0
	v_cndmask_b32_e64 v128, v129, v131, s[8:9]
	s_nop 1
	v_mov_b32_dpp v130, v128 quad_perm:[1,0,3,2] row_mask:0xf bank_mask:0xf bound_ctrl:1
	s_mov_b32 s8, 0x05040100
	s_mov_b32 s9, 0x07060302
	v_cndmask_b32_e32 v129, v129, v130, vcc
	v_cndmask_b32_e32 v131, v130, v131, vcc
	v_perm_b32 v128, v131, v129, s8
	v_perm_b32 v159, v131, v129, s9
	v_lshl_add_u64 v[130:131], v[164:165], 0, v[162:163]
	v_lshl_add_u64 v[130:131], v[132:133], 1, v[130:131]
	global_store_dword v[130:131], v128, off
	v_lshl_add_u64 v[128:129], v[130:131], 0, s[58:59]
	global_store_dword v[128:129], v159, off
	s_mov_b64 s[8:9], 0

.LBB0_414:
	v_and_b32_e32 v131, 1, v166
	v_cmp_eq_u32_e64 s[8:9], 0, v131
	v_cmp_eq_u32_e64 s[10:11], 1, v131
	v_cvt_pk_bf16_f32 v132, v124, v125
	v_cvt_pk_bf16_f32 v166, v126, v127
	s_nop 0
	v_cndmask_b32_e64 v131, v132, v166, s[8:9]
	s_nop 1
	v_mov_b32_dpp v161, v131 quad_perm:[1,0,3,2] row_mask:0xf bank_mask:0xf bound_ctrl:1
	s_mov_b32 s12, 0x05040100
	s_mov_b32 s13, 0x07060302
	v_cndmask_b32_e64 v132, v132, v161, s[10:11]
	v_cndmask_b32_e64 v166, v161, v166, s[10:11]
	v_perm_b32 v131, v166, v132, s12
	v_perm_b32 v160, v166, v132, s13
	v_and_b32_e32 v132, s44, v158
	s_add_u32 s38, s28, 0x6000000
	s_addc_u32 s39, s29, 0
	v_lshlrev_b32_e32 v132, 11, v132
	v_lshl_add_u64 v[166:167], s[38:39], 0, v[132:133]
	s_lshl_b32 s58, s45, 9
	v_lshl_add_u64 v[170:171], v[166:167], 0, s[58:59]
	s_lshl_b32 s58, s49, 1
	s_add_i32 s12, s58, -1
	v_mov_b32_e32 v132, s12
	v_cndmask_b32_e64 v132, v132, 0, s[8:9]
	v_lshl_add_u64 v[128:129], v[132:133], 1, v[128:129]
	global_store_dword v[128:129], v131, off
	v_lshl_add_u64 v[128:129], v[128:129], 0, s[58:59]
	global_store_dword v[128:129], v160, off
	v_cndmask_b32_e64 v128, 0, 1, s[2:3]
	s_lshl_b32 s55, s48, 1
	v_cmp_ne_u32_e64 s[12:13], 1, v128
	s_andn2_b64 vcc, exec, s[2:3]
	v_lshlrev_b32_e32 v128, 2, v159
	s_cbranch_vccnz .LBB0_424
	s_add_i32 s48, s55, s40
	s_ashr_i32 s49, s48, 31
	s_lshl_b64 s[48:49], s[48:49], 19
	v_lshl_add_u64 v[160:161], v[170:171], 0, s[48:49]
	v_mov_b32_e32 v129, v133
	v_lshl_add_u64 v[160:161], v[160:161], 0, v[128:129]
	global_store_dwordx4 v[160:161], v[124:127], off

.LBB0_428:
	v_cvt_pk_bf16_f32 v131, v120, v121
	v_cvt_pk_bf16_f32 v161, v122, v123
	s_nop 0
	v_cndmask_b32_e64 v129, v131, v161, s[8:9]
	s_nop 1
	v_mov_b32_dpp v132, v129 quad_perm:[1,0,3,2] row_mask:0xf bank_mask:0xf bound_ctrl:1
	s_mov_b32 s48, 0x05040100
	s_mov_b32 s49, 0x07060302
	v_cndmask_b32_e64 v131, v131, v132, s[10:11]
	v_cndmask_b32_e64 v161, v132, v161, s[10:11]
	v_perm_b32 v129, v161, v131, s48
	v_perm_b32 v168, v161, v131, s49
	s_lshl_b32 s58, s54, 1
	s_add_i32 s48, s58, -1
	v_mov_b32_e32 v131, s48
	v_cndmask_b32_e64 v132, v131, 0, s[8:9]
	v_lshl_add_u64 v[172:173], v[132:133], 1, v[172:173]
	global_store_dword v[172:173], v129, off
	v_lshl_add_u64 v[172:173], v[172:173], 0, s[58:59]
	s_and_b64 vcc, exec, s[12:13]
	global_store_dword v[172:173], v168, off
	s_cbranch_vccnz .LBB0_438
	s_add_i32 s48, s55, s40
	s_ashr_i32 s49, s48, 31
	s_lshl_b64 s[48:49], s[48:49], 19
	v_lshl_add_u64 v[168:169], v[170:171], 0, s[48:49]
	v_mov_b32_e32 v129, v133
	v_lshl_add_u64 v[168:169], v[168:169], 0, v[128:129]
	global_store_dwordx4 v[168:169], v[120:123], off offset:64

.LBB0_442:
	v_cvt_pk_bf16_f32 v131, v116, v117
	v_cvt_pk_bf16_f32 v164, v118, v119
	s_nop 0
	v_cndmask_b32_e64 v129, v131, v164, s[8:9]
	s_nop 1
	v_mov_b32_dpp v132, v129 quad_perm:[1,0,3,2] row_mask:0xf bank_mask:0xf bound_ctrl:1
	s_mov_b32 s48, 0x05040100
	s_mov_b32 s49, 0x07060302
	v_cndmask_b32_e64 v131, v131, v132, s[10:11]
	v_cndmask_b32_e64 v164, v132, v164, s[10:11]
	v_perm_b32 v129, v164, v131, s48
	v_perm_b32 v161, v164, v131, s49
	s_lshl_b32 s58, s54, 9
	v_lshl_add_u64 v[164:165], v[166:167], 0, s[58:59]
	s_lshl_b32 s58, s60, 1
	s_add_i32 s48, s58, -1
	v_mov_b32_e32 v131, s48
	v_cndmask_b32_e64 v132, v131, 0, s[8:9]
	v_lshl_add_u64 v[166:167], v[132:133], 1, v[170:171]
	global_store_dword v[166:167], v129, off
	v_lshl_add_u64 v[166:167], v[166:167], 0, s[58:59]
	s_and_b64 vcc, exec, s[12:13]
	s_mov_b64 s[48:49], -1
	global_store_dword v[166:167], v161, off
	s_cbranch_vccnz .LBB0_452
	s_add_i32 s48, s55, s40
	s_ashr_i32 s49, s48, 31
	s_lshl_b64 s[48:49], s[48:49], 19
	v_lshl_add_u64 v[166:167], v[164:165], 0, s[48:49]
	v_mov_b32_e32 v129, v133
	v_lshl_add_u64 v[166:167], v[166:167], 0, v[128:129]
	v_mov_b32_e32 v161, v133
	global_store_dwordx4 v[166:167], v[116:119], off
	v_lshl_add_u64 v[166:167], v[168:169], 0, v[160:161]
	s_mov_b64 s[48:49], 0

.LBB0_454:
	v_cvt_pk_bf16_f32 v131, v112, v113
	v_cvt_pk_bf16_f32 v161, v114, v115
	s_nop 0
	v_cndmask_b32_e64 v129, v131, v161, s[8:9]
	s_nop 1
	v_mov_b32_dpp v132, v129 quad_perm:[1,0,3,2] row_mask:0xf bank_mask:0xf bound_ctrl:1
	s_mov_b32 s48, 0x05040100
	s_mov_b32 s49, 0x07060302
	v_cndmask_b32_e64 v131, v131, v132, s[10:11]
	v_cndmask_b32_e64 v161, v132, v161, s[10:11]
	v_perm_b32 v129, v161, v131, s48
	v_perm_b32 v162, v161, v131, s49
	s_lshl_b32 s58, s58, 1
	s_add_i32 s48, s58, -1
	v_mov_b32_e32 v131, s48
	v_cndmask_b32_e64 v132, v131, 0, s[8:9]
	v_lshl_add_u64 v[166:167], v[132:133], 1, v[166:167]
	global_store_dword v[166:167], v129, off
	v_lshl_add_u64 v[166:167], v[166:167], 0, s[58:59]
	s_and_b64 vcc, exec, s[12:13]
	global_store_dword v[166:167], v162, off
	s_cbranch_vccnz .LBB0_464
	s_add_i32 s48, s55, s40
	s_ashr_i32 s49, s48, 31
	s_lshl_b64 s[48:49], s[48:49], 19
	v_lshl_add_u64 v[162:163], v[164:165], 0, s[48:49]
	v_mov_b32_e32 v129, v133
	v_lshl_add_u64 v[162:163], v[162:163], 0, v[128:129]
	global_store_dwordx4 v[162:163], v[112:115], off offset:64

.LBB0_468:
	v_cvt_pk_bf16_f32 v132, v108, v109
	v_cvt_pk_bf16_f32 v164, v110, v111
	s_nop 0
	v_cndmask_b32_e64 v131, v132, v164, s[8:9]
	s_nop 1
	v_mov_b32_dpp v161, v131 quad_perm:[1,0,3,2] row_mask:0xf bank_mask:0xf bound_ctrl:1
	s_mov_b32 s48, 0x05040100
	s_mov_b32 s49, 0x07060302
	v_cndmask_b32_e64 v132, v132, v161, s[10:11]
	v_cndmask_b32_e64 v164, v161, v164, s[10:11]
	v_perm_b32 v131, v164, v132, s48
	v_perm_b32 v163, v164, v132, s49
	s_lshl_b32 s48, s45, 7
	s_lshl_b32 s58, s48, 2
	s_lshl_b32 s48, s60, 1
	s_add_i32 s49, s48, -1
	v_lshlrev_b32_e32 v132, 11, v129
	v_mov_b32_e32 v129, s49
	v_lshl_add_u64 v[164:165], s[38:39], 0, v[132:133]
	v_cndmask_b32_e64 v132, v129, 0, s[8:9]
	v_lshl_add_u64 v[168:169], v[132:133], 1, v[168:169]
	s_mov_b32 s49, s59
	v_lshl_add_u64 v[166:167], v[164:165], 0, s[58:59]
	global_store_dword v[168:169], v131, off
	v_lshl_add_u64 v[168:169], v[168:169], 0, s[48:49]
	s_and_b64 vcc, exec, s[12:13]
	s_mov_b64 s[48:49], -1
	global_store_dword v[168:169], v163, off
	s_cbranch_vccnz .LBB0_478
	s_add_i32 s48, s55, s40
	s_ashr_i32 s49, s48, 31
	s_lshl_b64 s[48:49], s[48:49], 19
	v_lshl_add_u64 v[168:169], v[166:167], 0, s[48:49]
	s_lshl_b64 s[48:49], s[64:65], 1
	v_mov_b32_e32 v129, v133
	s_add_u32 s48, s46, s48
	v_lshl_add_u64 v[168:169], v[168:169], 0, v[128:129]
	s_addc_u32 s49, s47, s49
	v_mov_b32_e32 v161, v133
	global_store_dwordx4 v[168:169], v[108:111], off
	v_lshl_add_u64 v[168:169], s[48:49], 0, v[160:161]
	v_mov_b32_e32 v163, v133
	v_lshl_add_u64 v[168:169], v[168:169], 0, v[162:163]
	s_mov_b64 s[48:49], 0

.LBB0_480:
	v_cvt_pk_bf16_f32 v131, v104, v105
	v_cvt_pk_bf16_f32 v161, v106, v107
	s_nop 0
	v_cndmask_b32_e64 v129, v131, v161, s[8:9]
	s_nop 1
	v_mov_b32_dpp v132, v129 quad_perm:[1,0,3,2] row_mask:0xf bank_mask:0xf bound_ctrl:1
	s_mov_b32 s48, 0x05040100
	s_mov_b32 s49, 0x07060302
	v_cndmask_b32_e64 v131, v131, v132, s[10:11]
	v_cndmask_b32_e64 v161, v132, v161, s[10:11]
	v_perm_b32 v129, v161, v131, s48
	v_perm_b32 v163, v161, v131, s49
	s_lshl_b32 s48, s60, 1
	s_add_i32 s49, s48, -1
	v_mov_b32_e32 v131, s49
	v_cndmask_b32_e64 v132, v131, 0, s[8:9]
	v_lshl_add_u64 v[168:169], v[132:133], 1, v[168:169]
	s_mov_b32 s49, s59
	global_store_dword v[168:169], v129, off
	v_lshl_add_u64 v[168:169], v[168:169], 0, s[48:49]
	s_and_b64 vcc, exec, s[12:13]
	global_store_dword v[168:169], v163, off
	s_cbranch_vccnz .LBB0_494
	s_add_i32 s48, s55, s40
	s_ashr_i32 s49, s48, 31
	s_lshl_b64 s[48:49], s[48:49], 19
	v_lshl_add_u64 v[166:167], v[166:167], 0, s[48:49]
	v_mov_b32_e32 v129, v133
	v_lshl_add_u64 v[166:167], v[166:167], 0, v[128:129]
	global_store_dwordx4 v[166:167], v[104:107], off offset:64
	s_and_b64 vcc, exec, s[12:13]
	s_mov_b64 s[48:49], -1
	s_cbranch_vccz .LBB0_495

.LBB0_506:
	v_cvt_pk_bf16_f32 v131, v96, v97
	v_cvt_pk_bf16_f32 v161, v98, v99
	s_nop 0
	v_cndmask_b32_e64 v129, v131, v161, s[8:9]
	s_nop 1
	v_mov_b32_dpp v132, v129 quad_perm:[1,0,3,2] row_mask:0xf bank_mask:0xf bound_ctrl:1
	s_mov_b32 s82, 0x05040100
	s_mov_b32 s83, 0x07060302
	v_cndmask_b32_e64 v131, v131, v132, s[10:11]
	v_cndmask_b32_e64 v161, v132, v161, s[10:11]
	v_perm_b32 v129, v161, v131, s82
	v_perm_b32 v162, v161, v131, s83
	s_lshl_b32 s82, s49, 1
	s_add_i32 s49, s82, -1
	v_mov_b32_e32 v131, s49
	v_cndmask_b32_e64 v132, v131, 0, s[8:9]
	v_lshl_add_u64 v[166:167], v[132:133], 1, v[166:167]
	s_mov_b32 s83, s59
	global_store_dword v[166:167], v129, off
	v_lshl_add_u64 v[166:167], v[166:167], 0, s[82:83]
	s_and_b64 vcc, exec, s[12:13]
	global_store_dword v[166:167], v162, off
	s_cbranch_vccnz .LBB0_516
	s_add_i32 s82, s55, s40
	s_ashr_i32 s83, s82, 31
	s_lshl_b64 s[82:83], s[82:83], 19
	v_lshl_add_u64 v[162:163], v[164:165], 0, s[82:83]
	v_mov_b32_e32 v129, v133
	v_lshl_add_u64 v[162:163], v[162:163], 0, v[128:129]
	global_store_dwordx4 v[162:163], v[96:99], off offset:64

.LBB0_520:
	v_cvt_pk_bf16_f32 v132, v92, v93
	v_cvt_pk_bf16_f32 v166, v94, v95
	s_nop 0
	v_cndmask_b32_e64 v131, v132, v166, s[8:9]
	s_nop 1
	v_mov_b32_dpp v161, v131 quad_perm:[1,0,3,2] row_mask:0xf bank_mask:0xf bound_ctrl:1
	s_mov_b32 s82, 0x05040100
	s_mov_b32 s83, 0x07060302
	v_cndmask_b32_e64 v132, v132, v161, s[10:11]
	v_cndmask_b32_e64 v166, v161, v166, s[10:11]
	v_perm_b32 v131, v166, v132, s82
	v_perm_b32 v178, v166, v132, s83
	s_lshl_b32 s82, s49, 1
	s_add_i32 s49, s82, -1
	v_lshlrev_b32_e32 v132, 11, v129
	v_mov_b32_e32 v129, s49
	v_lshl_add_u64 v[166:167], s[38:39], 0, v[132:133]
	v_cndmask_b32_e64 v132, v129, 0, s[8:9]
	v_lshl_add_u64 v[172:173], v[132:133], 1, v[172:173]
	s_mov_b32 s83, s59
	v_lshl_add_u64 v[168:169], v[166:167], 0, s[58:59]
	global_store_dword v[172:173], v131, off
	v_lshl_add_u64 v[172:173], v[172:173], 0, s[82:83]
	s_and_b64 vcc, exec, s[12:13]
	s_mov_b64 s[82:83], -1
	global_store_dword v[172:173], v178, off
	s_cbranch_vccnz .LBB0_530
	s_add_i32 s82, s55, s40
	s_ashr_i32 s83, s82, 31
	s_lshl_b64 s[82:83], s[82:83], 19
	v_lshl_add_u64 v[172:173], v[168:169], 0, s[82:83]
	v_mov_b32_e32 v129, v133
	v_lshl_add_u64 v[172:173], v[172:173], 0, v[128:129]
	v_mov_b32_e32 v161, v133
	global_store_dwordx4 v[172:173], v[92:95], off
	v_lshl_add_u64 v[172:173], v[170:171], 0, v[160:161]
	s_mov_b64 s[82:83], 0

.LBB0_532:
	v_cvt_pk_bf16_f32 v131, v88, v89
	v_cvt_pk_bf16_f32 v161, v90, v91
	s_nop 0
	v_cndmask_b32_e64 v129, v131, v161, s[8:9]
	s_nop 1
	v_mov_b32_dpp v132, v129 quad_perm:[1,0,3,2] row_mask:0xf bank_mask:0xf bound_ctrl:1
	s_mov_b32 s82, 0x05040100
	s_mov_b32 s83, 0x07060302
	v_cndmask_b32_e64 v131, v131, v132, s[10:11]
	v_cndmask_b32_e64 v161, v132, v161, s[10:11]
	v_perm_b32 v129, v161, v131, s82
	v_perm_b32 v170, v161, v131, s83
	s_lshl_b32 s82, s49, 1
	s_add_i32 s49, s82, -1
	v_mov_b32_e32 v131, s49
	v_cndmask_b32_e64 v132, v131, 0, s[8:9]
	v_lshl_add_u64 v[172:173], v[132:133], 1, v[172:173]
	s_mov_b32 s83, s59
	global_store_dword v[172:173], v129, off
	v_lshl_add_u64 v[172:173], v[172:173], 0, s[82:83]
	s_and_b64 vcc, exec, s[12:13]
	global_store_dword v[172:173], v170, off
	s_cbranch_vccnz .LBB0_542
	s_add_i32 s82, s55, s40
	s_ashr_i32 s83, s82, 31
	s_lshl_b64 s[82:83], s[82:83], 19
	v_lshl_add_u64 v[168:169], v[168:169], 0, s[82:83]
	v_mov_b32_e32 v129, v133
	v_lshl_add_u64 v[168:169], v[168:169], 0, v[128:129]
	global_store_dwordx4 v[168:169], v[88:91], off offset:64

.LBB0_546:
	v_cvt_pk_bf16_f32 v131, v84, v85
	v_cvt_pk_bf16_f32 v164, v86, v87
	s_nop 0
	v_cndmask_b32_e64 v129, v131, v164, s[8:9]
	s_nop 1
	v_mov_b32_dpp v132, v129 quad_perm:[1,0,3,2] row_mask:0xf bank_mask:0xf bound_ctrl:1
	s_mov_b32 s82, 0x05040100
	s_mov_b32 s83, 0x07060302
	v_cndmask_b32_e64 v131, v131, v132, s[10:11]
	v_cndmask_b32_e64 v164, v132, v164, s[10:11]
	v_perm_b32 v129, v164, v131, s82
	v_perm_b32 v161, v164, v131, s83
	s_mov_b32 s49, s59
	s_lshl_b32 s82, s60, 1
	v_lshl_add_u64 v[164:165], v[166:167], 0, s[48:49]
	s_add_i32 s49, s82, -1
	v_mov_b32_e32 v131, s49
	v_cndmask_b32_e64 v132, v131, 0, s[8:9]
	v_lshl_add_u64 v[166:167], v[132:133], 1, v[170:171]
	s_mov_b32 s83, s59
	global_store_dword v[166:167], v129, off
	v_lshl_add_u64 v[166:167], v[166:167], 0, s[82:83]
	s_and_b64 vcc, exec, s[12:13]
	s_mov_b64 s[82:83], -1
	global_store_dword v[166:167], v161, off
	s_cbranch_vccnz .LBB0_556
	s_add_i32 s82, s55, s40
	s_ashr_i32 s83, s82, 31
	s_lshl_b64 s[82:83], s[82:83], 19
	v_lshl_add_u64 v[166:167], v[164:165], 0, s[82:83]
	v_mov_b32_e32 v129, v133
	v_lshl_add_u64 v[166:167], v[166:167], 0, v[128:129]
	v_mov_b32_e32 v161, v133
	global_store_dwordx4 v[166:167], v[84:87], off
	v_lshl_add_u64 v[166:167], v[168:169], 0, v[160:161]
	s_mov_b64 s[82:83], 0

.LBB0_558:
	v_cvt_pk_bf16_f32 v131, v80, v81
	v_cvt_pk_bf16_f32 v161, v82, v83
	s_nop 0
	v_cndmask_b32_e64 v129, v131, v161, s[8:9]
	s_nop 1
	v_mov_b32_dpp v132, v129 quad_perm:[1,0,3,2] row_mask:0xf bank_mask:0xf bound_ctrl:1
	s_mov_b32 s82, 0x05040100
	s_mov_b32 s83, 0x07060302
	v_cndmask_b32_e64 v131, v131, v132, s[10:11]
	v_cndmask_b32_e64 v161, v132, v161, s[10:11]
	v_perm_b32 v129, v161, v131, s82
	v_perm_b32 v162, v161, v131, s83
	s_lshl_b32 s82, s49, 1
	s_add_i32 s49, s82, -1
	v_mov_b32_e32 v131, s49
	v_cndmask_b32_e64 v132, v131, 0, s[8:9]
	v_lshl_add_u64 v[166:167], v[132:133], 1, v[166:167]
	s_mov_b32 s83, s59
	global_store_dword v[166:167], v129, off
	v_lshl_add_u64 v[166:167], v[166:167], 0, s[82:83]
	s_and_b64 vcc, exec, s[12:13]
	global_store_dword v[166:167], v162, off
	s_cbranch_vccnz .LBB0_568
	s_add_i32 s82, s55, s40
	s_ashr_i32 s83, s82, 31
	s_lshl_b64 s[82:83], s[82:83], 19
	v_lshl_add_u64 v[162:163], v[164:165], 0, s[82:83]
	v_mov_b32_e32 v129, v133
	v_lshl_add_u64 v[162:163], v[162:163], 0, v[128:129]
	global_store_dwordx4 v[162:163], v[80:83], off offset:64

.LBB0_572:
	v_cvt_pk_bf16_f32 v132, v76, v77
	v_cvt_pk_bf16_f32 v164, v78, v79
	s_nop 0
	v_cndmask_b32_e64 v131, v132, v164, s[8:9]
	s_nop 1
	v_mov_b32_dpp v161, v131 quad_perm:[1,0,3,2] row_mask:0xf bank_mask:0xf bound_ctrl:1
	s_mov_b32 s82, 0x05040100
	s_mov_b32 s83, 0x07060302
	v_cndmask_b32_e64 v132, v132, v161, s[10:11]
	v_cndmask_b32_e64 v164, v161, v164, s[10:11]
	v_perm_b32 v131, v164, v132, s82
	v_perm_b32 v163, v164, v132, s83
	s_lshl_b32 s82, s49, 1
	s_add_i32 s49, s82, -1
	v_lshlrev_b32_e32 v132, 11, v129
	v_mov_b32_e32 v129, s49
	v_lshl_add_u64 v[164:165], s[38:39], 0, v[132:133]
	v_cndmask_b32_e64 v132, v129, 0, s[8:9]
	v_lshl_add_u64 v[168:169], v[132:133], 1, v[168:169]
	s_mov_b32 s83, s59
	v_lshl_add_u64 v[166:167], v[164:165], 0, s[58:59]
	global_store_dword v[168:169], v131, off
	v_lshl_add_u64 v[168:169], v[168:169], 0, s[82:83]
	s_and_b64 vcc, exec, s[12:13]
	s_mov_b64 s[82:83], -1
	global_store_dword v[168:169], v163, off
	s_cbranch_vccnz .LBB0_582
	s_add_i32 s82, s55, s40
	s_ashr_i32 s83, s82, 31
	s_lshl_b64 s[82:83], s[82:83], 19
	s_lshl_b64 s[64:65], s[64:65], 1
	v_lshl_add_u64 v[168:169], v[166:167], 0, s[82:83]
	v_mov_b32_e32 v129, v133
	s_add_u32 s64, s46, s64
	v_lshl_add_u64 v[168:169], v[168:169], 0, v[128:129]
	s_addc_u32 s65, s47, s65
	v_mov_b32_e32 v161, v133
	global_store_dwordx4 v[168:169], v[76:79], off
	v_lshl_add_u64 v[168:169], s[64:65], 0, v[160:161]
	v_mov_b32_e32 v163, v133
	v_lshl_add_u64 v[168:169], v[168:169], 0, v[162:163]
	s_mov_b64 s[82:83], 0

.LBB0_584:
	v_cvt_pk_bf16_f32 v131, v72, v73
	v_cvt_pk_bf16_f32 v161, v74, v75
	s_nop 0
	v_cndmask_b32_e64 v129, v131, v161, s[8:9]
	s_nop 1
	v_mov_b32_dpp v132, v129 quad_perm:[1,0,3,2] row_mask:0xf bank_mask:0xf bound_ctrl:1
	s_mov_b32 s60, 0x05040100
	s_mov_b32 s61, 0x07060302
	v_cndmask_b32_e64 v131, v131, v132, s[10:11]
	v_cndmask_b32_e64 v161, v132, v161, s[10:11]
	v_perm_b32 v129, v161, v131, s60
	v_perm_b32 v163, v161, v131, s61
	s_lshl_b32 s60, s49, 1
	s_add_i32 s49, s60, -1
	v_mov_b32_e32 v131, s49
	v_cndmask_b32_e64 v132, v131, 0, s[8:9]
	v_lshl_add_u64 v[168:169], v[132:133], 1, v[168:169]
	s_mov_b32 s61, s59
	global_store_dword v[168:169], v129, off
	v_lshl_add_u64 v[168:169], v[168:169], 0, s[60:61]
	s_and_b64 vcc, exec, s[12:13]
	global_store_dword v[168:169], v163, off
	s_cbranch_vccnz .LBB0_598
	s_add_i32 s60, s55, s40
	s_ashr_i32 s61, s60, 31
	s_lshl_b64 s[60:61], s[60:61], 19
	v_lshl_add_u64 v[166:167], v[166:167], 0, s[60:61]
	v_mov_b32_e32 v129, v133
	v_lshl_add_u64 v[166:167], v[166:167], 0, v[128:129]
	global_store_dwordx4 v[166:167], v[72:75], off offset:64
	s_and_b64 vcc, exec, s[12:13]
	s_mov_b64 s[60:61], -1
	s_cbranch_vccz .LBB0_599

.LBB0_610:
	v_cvt_pk_bf16_f32 v131, v64, v65
	v_cvt_pk_bf16_f32 v161, v66, v67
	s_nop 0
	v_cndmask_b32_e64 v129, v131, v161, s[8:9]
	s_nop 1
	v_mov_b32_dpp v132, v129 quad_perm:[1,0,3,2] row_mask:0xf bank_mask:0xf bound_ctrl:1
	s_mov_b32 s60, 0x05040100
	s_mov_b32 s61, 0x07060302
	v_cndmask_b32_e64 v131, v131, v132, s[10:11]
	v_cndmask_b32_e64 v161, v132, v161, s[10:11]
	v_perm_b32 v129, v161, v131, s60
	v_perm_b32 v162, v161, v131, s61
	s_lshl_b32 s60, s49, 1
	s_add_i32 s49, s60, -1
	v_mov_b32_e32 v131, s49
	v_cndmask_b32_e64 v132, v131, 0, s[8:9]
	v_lshl_add_u64 v[166:167], v[132:133], 1, v[166:167]
	s_mov_b32 s61, s59
	global_store_dword v[166:167], v129, off
	v_lshl_add_u64 v[166:167], v[166:167], 0, s[60:61]
	s_and_b64 vcc, exec, s[12:13]
	global_store_dword v[166:167], v162, off
	s_cbranch_vccnz .LBB0_620
	s_add_i32 s60, s55, s40
	s_ashr_i32 s61, s60, 31
	s_lshl_b64 s[60:61], s[60:61], 19
	v_lshl_add_u64 v[162:163], v[164:165], 0, s[60:61]
	v_mov_b32_e32 v129, v133
	v_lshl_add_u64 v[162:163], v[162:163], 0, v[128:129]
	global_store_dwordx4 v[162:163], v[64:67], off offset:64

.LBB0_624:
	v_cvt_pk_bf16_f32 v132, v60, v61
	v_cvt_pk_bf16_f32 v171, v62, v63
	s_nop 0
	v_cndmask_b32_e64 v131, v132, v171, s[8:9]
	s_nop 1
	v_mov_b32_dpp v170, v131 quad_perm:[1,0,3,2] row_mask:0xf bank_mask:0xf bound_ctrl:1
	s_mov_b32 s6, 0x05040100
	s_mov_b32 s7, 0x07060302
	v_cndmask_b32_e64 v132, v132, v170, s[10:11]
	v_cndmask_b32_e64 v171, v170, v171, s[10:11]
	v_perm_b32 v131, v171, v132, s6
	v_perm_b32 v178, v171, v132, s7
	s_lshl_b32 s6, s45, 1
	s_add_i32 s7, s6, -1
	v_lshlrev_b32_e32 v132, 11, v129
	v_mov_b32_e32 v129, s7
	v_lshl_add_u64 v[170:171], s[38:39], 0, v[132:133]
	v_cndmask_b32_e64 v132, v129, 0, s[8:9]
	v_lshl_add_u64 v[162:163], v[132:133], 1, v[162:163]
	s_mov_b32 s7, s59
	v_lshlrev_b32_e32 v161, 1, v161
	global_store_dword v[162:163], v131, off
	v_lshl_add_u64 v[162:163], v[162:163], 0, s[6:7]
	global_store_dword v[162:163], v178, off
	v_add_u32_e32 v162, s40, v161
	v_lshl_add_u64 v[174:175], v[170:171], 0, s[58:59]
	s_mov_b64 s[6:7], -1
	s_and_b64 vcc, exec, s[12:13]
	v_ashrrev_i32_e32 v163, 31, v162
	s_cbranch_vccnz .LBB0_634
	v_lshlrev_b64 v[178:179], 19, v[162:163]
	v_lshl_add_u64 v[178:179], v[174:175], 0, v[178:179]
	v_mov_b32_e32 v129, v133
	v_lshl_add_u64 v[178:179], v[178:179], 0, v[128:129]
	v_mov_b32_e32 v161, v133
	global_store_dwordx4 v[178:179], v[60:63], off
	v_lshl_add_u64 v[178:179], v[176:177], 0, v[160:161]
	s_mov_b64 s[6:7], 0

.LBB0_636:
	v_cvt_pk_bf16_f32 v131, v56, v57
	v_cvt_pk_bf16_f32 v161, v58, v59
	s_nop 0
	v_cndmask_b32_e64 v129, v131, v161, s[8:9]
	s_nop 1
	v_mov_b32_dpp v132, v129 quad_perm:[1,0,3,2] row_mask:0xf bank_mask:0xf bound_ctrl:1
	s_mov_b32 s6, 0x05040100
	s_mov_b32 s7, 0x07060302
	v_cndmask_b32_e64 v131, v131, v132, s[10:11]
	v_cndmask_b32_e64 v161, v132, v161, s[10:11]
	v_perm_b32 v129, v161, v131, s6
	v_perm_b32 v176, v161, v131, s7
	s_lshl_b32 s6, s45, 1
	s_add_i32 s7, s6, -1
	v_mov_b32_e32 v131, s7
	v_cndmask_b32_e64 v132, v131, 0, s[8:9]
	v_lshl_add_u64 v[178:179], v[132:133], 1, v[178:179]
	s_mov_b32 s7, s59
	global_store_dword v[178:179], v129, off
	v_lshl_add_u64 v[178:179], v[178:179], 0, s[6:7]
	s_and_b64 vcc, exec, s[12:13]
	global_store_dword v[178:179], v176, off
	s_cbranch_vccnz .LBB0_646
	v_lshlrev_b64 v[176:177], 19, v[162:163]
	v_lshl_add_u64 v[174:175], v[174:175], 0, v[176:177]
	v_mov_b32_e32 v129, v133
	v_lshl_add_u64 v[174:175], v[174:175], 0, v[128:129]
	global_store_dwordx4 v[174:175], v[56:59], off offset:64

.LBB0_650:
	v_cvt_pk_bf16_f32 v131, v52, v53
	v_cvt_pk_bf16_f32 v161, v54, v55
	s_nop 0
	v_cndmask_b32_e64 v129, v131, v161, s[8:9]
	s_nop 1
	v_mov_b32_dpp v132, v129 quad_perm:[1,0,3,2] row_mask:0xf bank_mask:0xf bound_ctrl:1
	s_mov_b32 s6, 0x05040100
	s_mov_b32 s7, 0x07060302
	v_cndmask_b32_e64 v131, v131, v132, s[10:11]
	v_cndmask_b32_e64 v161, v132, v161, s[10:11]
	v_perm_b32 v129, v161, v131, s6
	v_perm_b32 v159, v161, v131, s7
	s_lshl_b32 s6, s45, 1
	s_add_i32 s7, s6, -1
	v_mov_b32_e32 v131, s7
	v_cndmask_b32_e64 v132, v131, 0, s[8:9]
	s_mov_b32 s49, s59
	v_lshl_add_u64 v[178:179], v[132:133], 1, v[178:179]
	s_mov_b32 s7, s59
	v_lshl_add_u64 v[170:171], v[170:171], 0, s[48:49]
	global_store_dword v[178:179], v129, off
	v_lshl_add_u64 v[178:179], v[178:179], 0, s[6:7]
	s_and_b64 vcc, exec, s[12:13]
	s_mov_b64 s[6:7], -1
	global_store_dword v[178:179], v159, off
	s_cbranch_vccnz .LBB0_660
	v_lshlrev_b64 v[178:179], 19, v[162:163]
	v_lshl_add_u64 v[178:179], v[170:171], 0, v[178:179]
	v_mov_b32_e32 v129, v133
	v_lshl_add_u64 v[178:179], v[178:179], 0, v[128:129]
	v_mov_b32_e32 v161, v133
	global_store_dwordx4 v[178:179], v[52:55], off
	v_lshl_add_u64 v[178:179], v[176:177], 0, v[160:161]
	s_mov_b64 s[6:7], 0

.LBB0_662:
	v_cvt_pk_bf16_f32 v131, v48, v49
	v_cvt_pk_bf16_f32 v161, v50, v51
	s_nop 0
	v_cndmask_b32_e64 v129, v131, v161, s[8:9]
	s_nop 1
	v_mov_b32_dpp v132, v129 quad_perm:[1,0,3,2] row_mask:0xf bank_mask:0xf bound_ctrl:1
	s_mov_b32 s6, 0x05040100
	s_mov_b32 s7, 0x07060302
	v_cndmask_b32_e64 v131, v131, v132, s[10:11]
	v_cndmask_b32_e64 v161, v132, v161, s[10:11]
	v_perm_b32 v129, v161, v131, s6
	v_perm_b32 v166, v161, v131, s7
	s_lshl_b32 s6, s45, 1
	s_add_i32 s7, s6, -1
	v_mov_b32_e32 v131, s7
	v_cndmask_b32_e64 v132, v131, 0, s[8:9]
	v_lshl_add_u64 v[168:169], v[132:133], 1, v[178:179]
	s_mov_b32 s7, s59
	global_store_dword v[168:169], v129, off
	v_lshl_add_u64 v[168:169], v[168:169], 0, s[6:7]
	s_and_b64 vcc, exec, s[12:13]
	global_store_dword v[168:169], v166, off
	s_cbranch_vccnz .LBB0_672
	v_lshlrev_b64 v[168:169], 19, v[162:163]
	v_lshl_add_u64 v[168:169], v[170:171], 0, v[168:169]
	v_mov_b32_e32 v129, v133
	v_lshl_add_u64 v[168:169], v[168:169], 0, v[128:129]
	global_store_dwordx4 v[168:169], v[48:51], off offset:64

.LBB0_676:
	v_cvt_pk_bf16_f32 v132, v44, v45
	v_cvt_pk_bf16_f32 v170, v46, v47
	s_nop 0
	v_cndmask_b32_e64 v131, v132, v170, s[8:9]
	s_nop 1
	v_mov_b32_dpp v161, v131 quad_perm:[1,0,3,2] row_mask:0xf bank_mask:0xf bound_ctrl:1
	s_mov_b32 s6, 0x05040100
	s_mov_b32 s7, 0x07060302
	v_cndmask_b32_e64 v132, v132, v161, s[10:11]
	v_cndmask_b32_e64 v170, v161, v170, s[10:11]
	v_perm_b32 v131, v170, v132, s6
	v_perm_b32 v166, v170, v132, s7
	s_lshl_b32 s6, s45, 1
	s_add_i32 s7, s6, -1
	v_lshlrev_b32_e32 v132, 11, v129
	v_mov_b32_e32 v129, s7
	v_lshl_add_u64 v[178:179], s[38:39], 0, v[132:133]
	v_cndmask_b32_e64 v132, v129, 0, s[8:9]
	v_lshl_add_u64 v[180:181], v[132:133], 1, v[180:181]
	s_mov_b32 s7, s59
	v_lshl_add_u64 v[170:171], v[178:179], 0, s[58:59]
	global_store_dword v[180:181], v131, off
	v_lshl_add_u64 v[180:181], v[180:181], 0, s[6:7]
	s_and_b64 vcc, exec, s[12:13]
	s_mov_b64 s[6:7], -1
	global_store_dword v[180:181], v166, off
	s_cbranch_vccnz .LBB0_686
	v_lshlrev_b64 v[180:181], 19, v[162:163]
	v_lshl_add_u64 v[180:181], v[170:171], 0, v[180:181]
	v_mov_b32_e32 v129, v133
	v_lshl_add_u64 v[180:181], v[180:181], 0, v[128:129]
	v_mov_b32_e32 v161, v133
	global_store_dwordx4 v[180:181], v[44:47], off
	v_lshl_add_u64 v[180:181], v[168:169], 0, v[160:161]
	v_mov_b32_e32 v177, v133
	v_lshl_add_u64 v[180:181], v[180:181], 0, v[176:177]
	s_mov_b64 s[6:7], 0

.LBB0_688:
	v_cvt_pk_bf16_f32 v131, v40, v41
	v_cvt_pk_bf16_f32 v161, v42, v43
	s_nop 0
	v_cndmask_b32_e64 v129, v131, v161, s[8:9]
	s_nop 1
	v_mov_b32_dpp v132, v129 quad_perm:[1,0,3,2] row_mask:0xf bank_mask:0xf bound_ctrl:1
	s_mov_b32 s6, 0x05040100
	s_mov_b32 s7, 0x07060302
	v_cndmask_b32_e64 v131, v131, v132, s[10:11]
	v_cndmask_b32_e64 v161, v132, v161, s[10:11]
	v_perm_b32 v129, v161, v131, s6
	v_perm_b32 v166, v161, v131, s7
	s_lshl_b32 s6, s45, 1
	s_add_i32 s7, s6, -1
	v_mov_b32_e32 v131, s7
	v_cndmask_b32_e64 v132, v131, 0, s[8:9]
	v_lshl_add_u64 v[180:181], v[132:133], 1, v[180:181]
	s_mov_b32 s7, s59
	global_store_dword v[180:181], v129, off
	v_lshl_add_u64 v[180:181], v[180:181], 0, s[6:7]
	s_and_b64 vcc, exec, s[12:13]
	global_store_dword v[180:181], v166, off
	s_cbranch_vccnz .LBB0_698
	v_lshlrev_b64 v[180:181], 19, v[162:163]
	v_lshl_add_u64 v[170:171], v[170:171], 0, v[180:181]
	v_mov_b32_e32 v129, v133
	v_lshl_add_u64 v[170:171], v[170:171], 0, v[128:129]
	global_store_dwordx4 v[170:171], v[40:43], off offset:64

.LBB0_702:
	v_cvt_pk_bf16_f32 v131, v36, v37
	v_cvt_pk_bf16_f32 v166, v38, v39
	s_nop 0
	v_cndmask_b32_e64 v129, v131, v166, s[8:9]
	s_nop 1
	v_mov_b32_dpp v132, v129 quad_perm:[1,0,3,2] row_mask:0xf bank_mask:0xf bound_ctrl:1
	s_mov_b32 s6, 0x05040100
	s_mov_b32 s7, 0x07060302
	v_cndmask_b32_e64 v131, v131, v132, s[10:11]
	v_cndmask_b32_e64 v166, v132, v166, s[10:11]
	v_perm_b32 v129, v166, v131, s6
	v_perm_b32 v161, v166, v131, s7
	s_lshl_b32 s6, s45, 1
	s_add_i32 s7, s6, -1
	v_mov_b32_e32 v131, s7
	v_cndmask_b32_e64 v132, v131, 0, s[8:9]
	s_mov_b32 s49, s59
	v_lshl_add_u64 v[180:181], v[132:133], 1, v[180:181]
	s_mov_b32 s7, s59
	v_lshl_add_u64 v[178:179], v[178:179], 0, s[48:49]
	global_store_dword v[180:181], v129, off
	v_lshl_add_u64 v[180:181], v[180:181], 0, s[6:7]
	s_and_b64 vcc, exec, s[12:13]
	s_mov_b64 s[6:7], -1
	global_store_dword v[180:181], v161, off
	s_cbranch_vccnz .LBB0_712
	v_lshlrev_b64 v[180:181], 19, v[162:163]
	v_lshl_add_u64 v[180:181], v[178:179], 0, v[180:181]
	v_mov_b32_e32 v129, v133
	v_lshl_add_u64 v[180:181], v[180:181], 0, v[128:129]
	v_mov_b32_e32 v161, v133
	global_store_dwordx4 v[180:181], v[36:39], off
	v_lshl_add_u64 v[180:181], v[170:171], 0, v[160:161]
	v_mov_b32_e32 v177, v133
	v_lshl_add_u64 v[180:181], v[180:181], 0, v[176:177]
	s_mov_b64 s[6:7], 0

.LBB0_714:
	v_cvt_pk_bf16_f32 v131, v32, v33
	v_cvt_pk_bf16_f32 v161, v34, v35
	s_nop 0
	v_cndmask_b32_e64 v129, v131, v161, s[8:9]
	s_nop 1
	v_mov_b32_dpp v132, v129 quad_perm:[1,0,3,2] row_mask:0xf bank_mask:0xf bound_ctrl:1
	s_mov_b32 s6, 0x05040100
	s_mov_b32 s7, 0x07060302
	v_cndmask_b32_e64 v131, v131, v132, s[10:11]
	v_cndmask_b32_e64 v161, v132, v161, s[10:11]
	v_perm_b32 v129, v161, v131, s6
	v_perm_b32 v166, v161, v131, s7
	s_lshl_b32 s6, s45, 1
	s_add_i32 s7, s6, -1
	v_mov_b32_e32 v131, s7
	v_cndmask_b32_e64 v132, v131, 0, s[8:9]
	v_lshl_add_u64 v[176:177], v[132:133], 1, v[180:181]
	s_mov_b32 s7, s59
	global_store_dword v[176:177], v129, off
	v_lshl_add_u64 v[176:177], v[176:177], 0, s[6:7]
	s_and_b64 vcc, exec, s[12:13]
	global_store_dword v[176:177], v166, off
	s_cbranch_vccnz .LBB0_724
	v_lshlrev_b64 v[176:177], 19, v[162:163]
	v_lshl_add_u64 v[176:177], v[178:179], 0, v[176:177]
	v_mov_b32_e32 v129, v133
	v_lshl_add_u64 v[176:177], v[176:177], 0, v[128:129]
	global_store_dwordx4 v[176:177], v[32:35], off offset:64

.LBB0_728:
	v_cvt_pk_bf16_f32 v132, v28, v29
	v_cvt_pk_bf16_f32 v178, v30, v31
	s_nop 0
	v_cndmask_b32_e64 v131, v132, v178, s[8:9]
	s_nop 1
	v_mov_b32_dpp v161, v131 quad_perm:[1,0,3,2] row_mask:0xf bank_mask:0xf bound_ctrl:1
	s_mov_b32 s6, 0x05040100
	s_mov_b32 s7, 0x07060302
	v_cndmask_b32_e64 v132, v132, v161, s[10:11]
	v_cndmask_b32_e64 v178, v161, v178, s[10:11]
	v_perm_b32 v131, v178, v132, s6
	v_perm_b32 v166, v178, v132, s7
	s_lshl_b32 s6, s45, 1
	s_add_i32 s7, s6, -1
	v_lshlrev_b32_e32 v132, 11, v129
	v_mov_b32_e32 v129, s7
	v_lshl_add_u64 v[178:179], s[38:39], 0, v[132:133]
	v_cndmask_b32_e64 v132, v129, 0, s[8:9]
	v_lshl_add_u64 v[184:185], v[132:133], 1, v[184:185]
	s_mov_b32 s7, s59
	v_lshl_add_u64 v[180:181], v[178:179], 0, s[58:59]
	global_store_dword v[184:185], v131, off
	v_lshl_add_u64 v[184:185], v[184:185], 0, s[6:7]
	s_and_b64 vcc, exec, s[12:13]
	s_mov_b64 s[6:7], -1
	global_store_dword v[184:185], v166, off
	s_cbranch_vccnz .LBB0_738
	v_lshlrev_b64 v[184:185], 19, v[162:163]
	v_lshl_add_u64 v[184:185], v[180:181], 0, v[184:185]
	v_mov_b32_e32 v129, v133
	v_lshl_add_u64 v[184:185], v[184:185], 0, v[128:129]
	v_mov_b32_e32 v161, v133
	global_store_dwordx4 v[184:185], v[28:31], off
	v_lshl_add_u64 v[184:185], v[182:183], 0, v[160:161]
	s_mov_b64 s[6:7], 0

.LBB0_740:
	v_cvt_pk_bf16_f32 v131, v24, v25
	v_cvt_pk_bf16_f32 v161, v26, v27
	s_nop 0
	v_cndmask_b32_e64 v129, v131, v161, s[8:9]
	s_nop 1
	v_mov_b32_dpp v132, v129 quad_perm:[1,0,3,2] row_mask:0xf bank_mask:0xf bound_ctrl:1
	s_mov_b32 s6, 0x05040100
	s_mov_b32 s7, 0x07060302
	v_cndmask_b32_e64 v131, v131, v132, s[10:11]
	v_cndmask_b32_e64 v161, v132, v161, s[10:11]
	v_perm_b32 v129, v161, v131, s6
	v_perm_b32 v166, v161, v131, s7
	s_lshl_b32 s6, s45, 1
	s_add_i32 s7, s6, -1
	v_mov_b32_e32 v131, s7
	v_cndmask_b32_e64 v132, v131, 0, s[8:9]
	v_lshl_add_u64 v[182:183], v[132:133], 1, v[184:185]
	s_mov_b32 s7, s59
	global_store_dword v[182:183], v129, off
	v_lshl_add_u64 v[182:183], v[182:183], 0, s[6:7]
	s_and_b64 vcc, exec, s[12:13]
	global_store_dword v[182:183], v166, off
	s_cbranch_vccnz .LBB0_750
	v_lshlrev_b64 v[182:183], 19, v[162:163]
	v_lshl_add_u64 v[180:181], v[180:181], 0, v[182:183]
	v_mov_b32_e32 v129, v133
	v_lshl_add_u64 v[180:181], v[180:181], 0, v[128:129]
	global_store_dwordx4 v[180:181], v[24:27], off offset:64

.LBB0_754:
	v_cvt_pk_bf16_f32 v131, v20, v21
	v_cvt_pk_bf16_f32 v166, v22, v23
	s_nop 0
	v_cndmask_b32_e64 v129, v131, v166, s[8:9]
	s_nop 1
	v_mov_b32_dpp v132, v129 quad_perm:[1,0,3,2] row_mask:0xf bank_mask:0xf bound_ctrl:1
	s_mov_b32 s6, 0x05040100
	s_mov_b32 s7, 0x07060302
	v_cndmask_b32_e64 v131, v131, v132, s[10:11]
	v_cndmask_b32_e64 v166, v132, v166, s[10:11]
	v_perm_b32 v129, v166, v131, s6
	v_perm_b32 v161, v166, v131, s7
	s_lshl_b32 s6, s45, 1
	s_add_i32 s7, s6, -1
	v_mov_b32_e32 v131, s7
	s_mov_b32 s49, s59
	v_cndmask_b32_e64 v132, v131, 0, s[8:9]
	v_lshl_add_u64 v[174:175], v[178:179], 0, s[48:49]
	v_lshl_add_u64 v[178:179], v[132:133], 1, v[180:181]
	s_mov_b32 s7, s59
	global_store_dword v[178:179], v129, off
	v_lshl_add_u64 v[178:179], v[178:179], 0, s[6:7]
	s_and_b64 vcc, exec, s[12:13]
	s_mov_b64 s[6:7], -1
	global_store_dword v[178:179], v161, off
	s_cbranch_vccnz .LBB0_764
	v_lshlrev_b64 v[178:179], 19, v[162:163]
	v_lshl_add_u64 v[178:179], v[174:175], 0, v[178:179]
	v_mov_b32_e32 v129, v133
	v_lshl_add_u64 v[178:179], v[178:179], 0, v[128:129]
	v_mov_b32_e32 v161, v133
	global_store_dwordx4 v[178:179], v[20:23], off
	v_lshl_add_u64 v[178:179], v[176:177], 0, v[160:161]
	s_mov_b64 s[6:7], 0

.LBB0_766:
	v_cvt_pk_bf16_f32 v131, v16, v17
	v_cvt_pk_bf16_f32 v161, v18, v19
	s_nop 0
	v_cndmask_b32_e64 v129, v131, v161, s[8:9]
	s_nop 1
	v_mov_b32_dpp v132, v129 quad_perm:[1,0,3,2] row_mask:0xf bank_mask:0xf bound_ctrl:1
	s_mov_b32 s6, 0x05040100
	s_mov_b32 s7, 0x07060302
	v_cndmask_b32_e64 v131, v131, v132, s[10:11]
	v_cndmask_b32_e64 v161, v132, v161, s[10:11]
	v_perm_b32 v129, v161, v131, s6
	v_perm_b32 v166, v161, v131, s7
	s_lshl_b32 s6, s45, 1
	s_add_i32 s7, s6, -1
	v_mov_b32_e32 v131, s7
	v_cndmask_b32_e64 v132, v131, 0, s[8:9]
	v_lshl_add_u64 v[172:173], v[132:133], 1, v[178:179]
	s_mov_b32 s7, s59
	global_store_dword v[172:173], v129, off
	v_lshl_add_u64 v[172:173], v[172:173], 0, s[6:7]
	s_and_b64 vcc, exec, s[12:13]
	global_store_dword v[172:173], v166, off
	s_cbranch_vccnz .LBB0_776
	v_lshlrev_b64 v[172:173], 19, v[162:163]
	v_lshl_add_u64 v[172:173], v[174:175], 0, v[172:173]
	v_mov_b32_e32 v129, v133
	v_lshl_add_u64 v[172:173], v[172:173], 0, v[128:129]
	global_store_dwordx4 v[172:173], v[16:19], off offset:64

.LBB0_780:
	v_cvt_pk_bf16_f32 v132, v12, v13
	v_cvt_pk_bf16_f32 v173, v14, v15
	s_nop 0
	v_cndmask_b32_e64 v131, v132, v173, s[8:9]
	s_nop 1
	v_mov_b32_dpp v161, v131 quad_perm:[1,0,3,2] row_mask:0xf bank_mask:0xf bound_ctrl:1
	s_mov_b32 s6, 0x05040100
	s_mov_b32 s7, 0x07060302
	v_cndmask_b32_e64 v132, v132, v161, s[10:11]
	v_cndmask_b32_e64 v173, v161, v173, s[10:11]
	v_perm_b32 v131, v173, v132, s6
	v_perm_b32 v166, v173, v132, s7
	v_lshlrev_b32_e32 v132, 11, v129
	v_lshl_add_u64 v[174:175], s[38:39], 0, v[132:133]
	v_lshl_add_u64 v[176:177], v[174:175], 0, s[58:59]
	s_lshl_b32 s58, s44, 1
	s_add_i32 s6, s58, -1
	v_mov_b32_e32 v129, s6
	v_cndmask_b32_e64 v132, v129, 0, s[8:9]
	v_lshl_add_u64 v[178:179], v[132:133], 1, v[178:179]
	global_store_dword v[178:179], v131, off
	v_lshl_add_u64 v[178:179], v[178:179], 0, s[58:59]
	s_and_b64 vcc, exec, s[12:13]
	s_mov_b64 s[6:7], -1
	global_store_dword v[178:179], v166, off
	s_cbranch_vccnz .LBB0_790
	v_lshlrev_b64 v[178:179], 19, v[162:163]
	v_lshl_add_u64 v[178:179], v[176:177], 0, v[178:179]
	v_mov_b32_e32 v129, v133
	v_mov_b32_e32 v161, v133
	v_lshl_add_u64 v[178:179], v[178:179], 0, v[128:129]
	v_lshl_add_u64 v[168:169], v[168:169], 0, v[160:161]
	v_mov_b32_e32 v173, v133
	global_store_dwordx4 v[178:179], v[12:15], off
	v_lshl_add_u64 v[178:179], v[168:169], 0, v[172:173]
	s_mov_b64 s[6:7], 0

.LBB0_792:
	v_cvt_pk_bf16_f32 v131, v8, v9
	v_cvt_pk_bf16_f32 v161, v10, v11
	s_nop 0
	v_cndmask_b32_e64 v129, v131, v161, s[8:9]
	s_nop 1
	v_mov_b32_dpp v132, v129 quad_perm:[1,0,3,2] row_mask:0xf bank_mask:0xf bound_ctrl:1
	s_mov_b32 s6, 0x05040100
	s_mov_b32 s7, 0x07060302
	v_cndmask_b32_e64 v131, v131, v132, s[10:11]
	v_cndmask_b32_e64 v161, v132, v161, s[10:11]
	v_perm_b32 v129, v161, v131, s6
	v_perm_b32 v164, v161, v131, s7
	s_lshl_b32 s58, s38, 1
	s_add_i32 s6, s58, -1
	v_mov_b32_e32 v131, s6
	v_cndmask_b32_e64 v132, v131, 0, s[8:9]
	v_lshl_add_u64 v[168:169], v[132:133], 1, v[178:179]
	global_store_dword v[168:169], v129, off
	v_lshl_add_u64 v[168:169], v[168:169], 0, s[58:59]
	s_and_b64 vcc, exec, s[12:13]
	global_store_dword v[168:169], v164, off
	s_cbranch_vccnz .LBB0_806
	v_lshlrev_b64 v[164:165], 19, v[162:163]
	v_lshl_add_u64 v[164:165], v[176:177], 0, v[164:165]
	v_mov_b32_e32 v129, v133
	v_lshl_add_u64 v[164:165], v[164:165], 0, v[128:129]
	global_store_dwordx4 v[164:165], v[8:11], off offset:64
	s_and_b64 vcc, exec, s[12:13]
	s_mov_b64 s[6:7], -1
	s_cbranch_vccz .LBB0_807

.LBB0_818:
	v_cvt_pk_bf16_f32 v132, v0, v1
	v_cvt_pk_bf16_f32 v160, v2, v3
	s_nop 0
	v_cndmask_b32_e64 v129, v132, v160, s[8:9]
	s_nop 1
	v_mov_b32_dpp v159, v129 quad_perm:[1,0,3,2] row_mask:0xf bank_mask:0xf bound_ctrl:1
	s_mov_b32 s6, 0x05040100
	s_mov_b32 s7, 0x07060302
	v_cndmask_b32_e64 v132, v132, v159, s[10:11]
	v_cndmask_b32_e64 v160, v159, v160, s[10:11]
	v_perm_b32 v129, v160, v132, s6
	v_perm_b32 v161, v160, v132, s7
	s_lshl_b32 s58, s38, 1
	s_add_i32 s6, s58, -1
	v_mov_b32_e32 v132, s6
	v_cndmask_b32_e64 v132, v132, 0, s[8:9]
	v_lshl_add_u64 v[164:165], v[132:133], 1, v[164:165]
	global_store_dword v[164:165], v129, off
	v_lshl_add_u64 v[164:165], v[164:165], 0, s[58:59]
	s_and_b64 vcc, exec, s[12:13]
	global_store_dword v[164:165], v161, off
	s_cbranch_vccnz .LBB0_828
	v_lshlrev_b64 v[160:161], 19, v[162:163]
	v_lshl_add_u64 v[130:131], v[130:131], 0, v[160:161]
	v_mov_b32_e32 v129, v133
	v_lshl_add_u64 v[128:129], v[130:131], 0, v[128:129]
	global_store_dwordx4 v[128:129], v[0:3], off offset:64

.LBB0_1024:
	s_and_b64 vcc, exec, s[2:3]
	s_cbranch_vccz .LBB0_141
	s_lshl_b32 s58, s19, 8
	v_lshl_add_u64 v[0:1], v[8:9], 0, s[58:59]
	global_store_dwordx2 v[0:1], v[10:11], off
	global_store_dwordx2 v[0:1], v[12:13], off offset:32
	s_branch .LBB0_141
	s_nop 0
	s_nop 0
	s_nop 0
	s_nop 0
	s_nop 0
	s_nop 0
	s_nop 0
	s_nop 0
	s_nop 0
	s_nop 0

.LBB0_1234:
	s_add_i32 s40, s10, 2
	s_add_u32 s12, s8, 0x80
	s_addc_u32 s11, s9, 0
	s_add_i32 s41, 0, 0x10000
	v_add_u32_e32 v152, s41, v154
	ds_read_b128 v[156:159], v152
	ds_read_b128 v[160:163], v152 offset:1024
	ds_read_b128 v[164:167], v152 offset:2048
	ds_read_b128 v[168:171], v152 offset:3072
	s_cmp_eq_u32 s29, s10
	s_cselect_b32 s10, s2, s12
	s_cselect_b32 s11, s3, s11
	s_cselect_b32 s13, s7, s39
	s_cselect_b32 s12, s6, s38
	v_lshl_add_u64 v[152:153], s[8:9], 0, v[130:131]
	s_add_i32 m0, s22, 0xc000
	ds_read_b128 v[172:175], v155
	ds_read_b128 v[180:183], v155 offset:2048
	ds_read_b128 v[188:191], v155 offset:4096
	ds_read_b128 v[220:223], v155 offset:6144
	ds_read_b128 v[176:179], v155 offset:1024
	ds_read_b128 v[184:187], v155 offset:3072
	ds_read_b128 v[216:219], v155 offset:5120
	ds_read_b128 v[224:227], v155 offset:7168
	global_load_lds_dwordx4 v[152:153], off
	v_lshl_add_u64 v[152:153], s[8:9], 0, v[150:151]
	s_add_i32 m0, s22, 0xe000
	s_nop 0
	global_load_lds_dwordx4 v[152:153], off
	s_waitcnt lgkmcnt(8)
	s_barrier
	s_waitcnt lgkmcnt(4)
	s_setprio 1
	v_mfma_f32_16x16x32_bf16 v[124:127], v[156:159], v[172:175], v[124:127]
	v_mfma_f32_16x16x32_bf16 v[120:123], v[164:167], v[172:175], v[120:123]
	v_mfma_f32_16x16x32_bf16 v[116:119], v[156:159], v[180:183], v[116:119]
	v_mfma_f32_16x16x32_bf16 v[108:111], v[164:167], v[180:183], v[108:111]
	v_mfma_f32_16x16x32_bf16 v[100:103], v[156:159], v[188:191], v[100:103]
	v_mfma_f32_16x16x32_bf16 v[92:95], v[164:167], v[188:191], v[92:95]
	v_mfma_f32_16x16x32_bf16 v[84:87], v[156:159], v[220:223], v[84:87]
	v_mfma_f32_16x16x32_bf16 v[76:79], v[164:167], v[220:223], v[76:79]
	s_waitcnt lgkmcnt(0)
	v_mfma_f32_16x16x32_bf16 v[124:127], v[160:163], v[176:179], v[124:127]
	v_mfma_f32_16x16x32_bf16 v[120:123], v[168:171], v[176:179], v[120:123]
	v_mfma_f32_16x16x32_bf16 v[116:119], v[160:163], v[184:187], v[116:119]
	v_mfma_f32_16x16x32_bf16 v[108:111], v[168:171], v[184:187], v[108:111]
	v_mfma_f32_16x16x32_bf16 v[100:103], v[160:163], v[216:219], v[100:103]
	v_mfma_f32_16x16x32_bf16 v[92:95], v[168:171], v[216:219], v[92:95]
	v_mfma_f32_16x16x32_bf16 v[84:87], v[160:163], v[224:227], v[84:87]
	v_mfma_f32_16x16x32_bf16 v[76:79], v[168:171], v[224:227], v[76:79]
	s_setprio 0
	s_barrier
	s_add_i32 s42, 0, 0x14000
	v_add_u32_e32 v152, s42, v154
	s_add_i32 s41, s41, s19
	ds_read_b128 v[228:231], v152
	ds_read_b128 v[236:239], v152 offset:2048
	ds_read_b128 v[232:235], v152 offset:1024
	ds_read_b128 v[240:243], v152 offset:3072
	v_lshl_add_u64 v[152:153], s[12:13], 0, v[132:133]
	s_mov_b32 m0, s41
	v_lshl_add_u64 v[244:245], s[12:13], 0, v[128:129]
	global_load_lds_dwordx4 v[152:153], off
	s_add_i32 m0, s41, 0x2000
	s_nop 0
	global_load_lds_dwordx4 v[244:245], off
	s_barrier
	s_waitcnt lgkmcnt(2)
	s_setprio 1
	v_mfma_f32_16x16x32_bf16 v[112:115], v[228:231], v[172:175], v[112:115]
	v_mfma_f32_16x16x32_bf16 v[104:107], v[236:239], v[172:175], v[104:107]
	v_mfma_f32_16x16x32_bf16 v[96:99], v[228:231], v[180:183], v[96:99]
	v_mfma_f32_16x16x32_bf16 v[88:91], v[236:239], v[180:183], v[88:91]
	v_mfma_f32_16x16x32_bf16 v[80:83], v[228:231], v[188:191], v[80:83]
	v_mfma_f32_16x16x32_bf16 v[72:75], v[236:239], v[188:191], v[72:75]
	v_mfma_f32_16x16x32_bf16 v[68:71], v[228:231], v[220:223], v[68:71]
	v_mfma_f32_16x16x32_bf16 v[64:67], v[236:239], v[220:223], v[64:67]
	s_waitcnt lgkmcnt(0)
	v_mfma_f32_16x16x32_bf16 v[112:115], v[232:235], v[176:179], v[112:115]
	v_mfma_f32_16x16x32_bf16 v[104:107], v[240:243], v[176:179], v[104:107]
	v_mfma_f32_16x16x32_bf16 v[96:99], v[232:235], v[184:187], v[96:99]
	v_mfma_f32_16x16x32_bf16 v[88:91], v[240:243], v[184:187], v[88:91]
	v_mfma_f32_16x16x32_bf16 v[80:83], v[232:235], v[216:219], v[80:83]
	v_mfma_f32_16x16x32_bf16 v[72:75], v[240:243], v[216:219], v[72:75]
	v_mfma_f32_16x16x32_bf16 v[68:71], v[232:235], v[224:227], v[68:71]
	v_mfma_f32_16x16x32_bf16 v[64:67], v[240:243], v[224:227], v[64:67]
	s_setprio 0
	s_mov_b32 m0, s22
	v_lshl_add_u64 v[246:247], s[10:11], 0, v[132:133]
	s_barrier
	ds_read_b128 v[172:175], v155 offset:16384
	ds_read_b128 v[180:183], v155 offset:18432
	ds_read_b128 v[188:191], v155 offset:20480
	ds_read_b128 v[220:223], v155 offset:22528
	ds_read_b128 v[176:179], v155 offset:17408
	ds_read_b128 v[184:187], v155 offset:19456
	ds_read_b128 v[216:219], v155 offset:21504
	ds_read_b128 v[224:227], v155 offset:23552
	global_load_lds_dwordx4 v[246:247], off
	v_lshl_add_u64 v[248:249], s[10:11], 0, v[128:129]
	s_mov_b32 m0, s23
	s_nop 0
	global_load_lds_dwordx4 v[248:249], off
	s_barrier
	s_waitcnt lgkmcnt(4)
	s_setprio 1
	v_mfma_f32_16x16x32_bf16 v[60:63], v[156:159], v[172:175], v[60:63]
	v_mfma_f32_16x16x32_bf16 v[56:59], v[164:167], v[172:175], v[56:59]
	v_mfma_f32_16x16x32_bf16 v[52:55], v[156:159], v[180:183], v[52:55]
	v_mfma_f32_16x16x32_bf16 v[44:47], v[164:167], v[180:183], v[44:47]
	v_mfma_f32_16x16x32_bf16 v[36:39], v[156:159], v[188:191], v[36:39]
	v_mfma_f32_16x16x32_bf16 v[28:31], v[164:167], v[188:191], v[28:31]
	v_mfma_f32_16x16x32_bf16 v[20:23], v[156:159], v[220:223], v[20:23]
	v_mfma_f32_16x16x32_bf16 v[12:15], v[164:167], v[220:223], v[12:15]
	s_waitcnt lgkmcnt(0)
	v_mfma_f32_16x16x32_bf16 v[60:63], v[160:163], v[176:179], v[60:63]
	v_mfma_f32_16x16x32_bf16 v[56:59], v[168:171], v[176:179], v[56:59]
	v_mfma_f32_16x16x32_bf16 v[52:55], v[160:163], v[184:187], v[52:55]
	v_mfma_f32_16x16x32_bf16 v[44:47], v[168:171], v[184:187], v[44:47]
	v_mfma_f32_16x16x32_bf16 v[36:39], v[160:163], v[216:219], v[36:39]
	v_mfma_f32_16x16x32_bf16 v[28:31], v[168:171], v[216:219], v[28:31]
	v_mfma_f32_16x16x32_bf16 v[20:23], v[160:163], v[224:227], v[20:23]
	v_mfma_f32_16x16x32_bf16 v[12:15], v[168:171], v[224:227], v[12:15]
	s_setprio 0
	s_barrier
	s_add_u32 s12, s12, s58
	s_addc_u32 s13, s13, 0
	s_add_i32 s41, s42, s19
	v_lshl_add_u64 v[250:251], s[12:13], 0, v[132:133]
	s_mov_b32 m0, s41
	v_lshl_add_u64 v[252:253], s[12:13], 0, v[128:129]
	global_load_lds_dwordx4 v[250:251], off
	s_add_i32 m0, s41, 0x2000
	s_nop 0
	global_load_lds_dwordx4 v[252:253], off
	s_waitcnt vmcnt(6)
	s_barrier
	s_setprio 1
	v_mfma_f32_16x16x32_bf16 v[48:51], v[228:231], v[172:175], v[48:51]
	v_mfma_f32_16x16x32_bf16 v[40:43], v[236:239], v[172:175], v[40:43]
	v_mfma_f32_16x16x32_bf16 v[32:35], v[228:231], v[180:183], v[32:35]
	v_mfma_f32_16x16x32_bf16 v[24:27], v[236:239], v[180:183], v[24:27]
	v_mfma_f32_16x16x32_bf16 v[16:19], v[228:231], v[188:191], v[16:19]
	v_mfma_f32_16x16x32_bf16 v[8:11], v[236:239], v[188:191], v[8:11]
	v_mfma_f32_16x16x32_bf16 v[4:7], v[228:231], v[220:223], v[4:7]
	v_mfma_f32_16x16x32_bf16 v[0:3], v[236:239], v[220:223], v[0:3]
	v_mfma_f32_16x16x32_bf16 v[48:51], v[232:235], v[176:179], v[48:51]
	v_mfma_f32_16x16x32_bf16 v[40:43], v[240:243], v[176:179], v[40:43]
	v_mfma_f32_16x16x32_bf16 v[32:35], v[232:235], v[184:187], v[32:35]
	v_mfma_f32_16x16x32_bf16 v[24:27], v[240:243], v[184:187], v[24:27]
	v_mfma_f32_16x16x32_bf16 v[16:19], v[232:235], v[216:219], v[16:19]
	v_mfma_f32_16x16x32_bf16 v[8:11], v[240:243], v[216:219], v[8:11]
	v_mfma_f32_16x16x32_bf16 v[4:7], v[232:235], v[224:227], v[4:7]
	v_mfma_f32_16x16x32_bf16 v[0:3], v[240:243], v[224:227], v[0:3]
	s_setprio 0
	s_add_i32 s12, 0, 0x18000
	v_add_u32_e32 v168, s12, v154
	s_barrier
	ds_read_b128 v[156:159], v168
	ds_read_b128 v[160:163], v168 offset:1024
	ds_read_b128 v[164:167], v168 offset:2048
	ds_read_b128 v[168:171], v168 offset:3072
	s_add_u32 s10, s10, s58
	s_addc_u32 s11, s11, 0
	s_mov_b32 m0, s24
	v_lshl_add_u64 v[228:229], s[10:11], 0, v[132:133]
	ds_read_b128 v[172:175], v155 offset:32768
	ds_read_b128 v[180:183], v155 offset:34816
	ds_read_b128 v[188:191], v155 offset:36864
	ds_read_b128 v[220:223], v155 offset:38912
	ds_read_b128 v[176:179], v155 offset:33792
	ds_read_b128 v[184:187], v155 offset:35840
	ds_read_b128 v[216:219], v155 offset:37888
	ds_read_b128 v[224:227], v155 offset:39936
	global_load_lds_dwordx4 v[228:229], off
	v_lshl_add_u64 v[228:229], s[10:11], 0, v[128:129]
	s_mov_b32 m0, s25
	s_nop 0
	global_load_lds_dwordx4 v[228:229], off
	s_waitcnt lgkmcnt(8)
	s_barrier
	s_waitcnt lgkmcnt(4)
	s_setprio 1
	v_mfma_f32_16x16x32_bf16 v[124:127], v[156:159], v[172:175], v[124:127]
	v_mfma_f32_16x16x32_bf16 v[120:123], v[164:167], v[172:175], v[120:123]
	v_mfma_f32_16x16x32_bf16 v[116:119], v[156:159], v[180:183], v[116:119]
	v_mfma_f32_16x16x32_bf16 v[108:111], v[164:167], v[180:183], v[108:111]
	v_mfma_f32_16x16x32_bf16 v[100:103], v[156:159], v[188:191], v[100:103]
	v_mfma_f32_16x16x32_bf16 v[92:95], v[164:167], v[188:191], v[92:95]
	v_mfma_f32_16x16x32_bf16 v[84:87], v[156:159], v[220:223], v[84:87]
	v_mfma_f32_16x16x32_bf16 v[76:79], v[164:167], v[220:223], v[76:79]
	s_waitcnt lgkmcnt(0)
	v_mfma_f32_16x16x32_bf16 v[124:127], v[160:163], v[176:179], v[124:127]
	v_mfma_f32_16x16x32_bf16 v[120:123], v[168:171], v[176:179], v[120:123]
	v_mfma_f32_16x16x32_bf16 v[116:119], v[160:163], v[184:187], v[116:119]
	v_mfma_f32_16x16x32_bf16 v[108:111], v[168:171], v[184:187], v[108:111]
	v_mfma_f32_16x16x32_bf16 v[100:103], v[160:163], v[216:219], v[100:103]
	v_mfma_f32_16x16x32_bf16 v[92:95], v[168:171], v[216:219], v[92:95]
	v_mfma_f32_16x16x32_bf16 v[84:87], v[160:163], v[224:227], v[84:87]
	v_mfma_f32_16x16x32_bf16 v[76:79], v[168:171], v[224:227], v[76:79]
	s_setprio 0
	s_barrier
	s_add_i32 s10, 0, 0x1c000
	s_add_i32 s11, s12, s19
	v_add_u32_e32 v200, s10, v154
	v_lshl_add_u64 v[152:153], v[152:153], 0, s[66:67]
	s_mov_b32 m0, s11
	ds_read_b128 v[228:231], v200
	ds_read_b128 v[236:239], v200 offset:2048
	ds_read_b128 v[232:235], v200 offset:1024
	ds_read_b128 v[240:243], v200 offset:3072
	global_load_lds_dwordx4 v[152:153], off
	v_lshl_add_u64 v[152:153], v[244:245], 0, s[66:67]
	s_add_i32 m0, s11, 0x2000
	s_nop 0
	global_load_lds_dwordx4 v[152:153], off
	s_barrier
	s_waitcnt lgkmcnt(2)
	s_setprio 1
	v_mfma_f32_16x16x32_bf16 v[112:115], v[228:231], v[172:175], v[112:115]
	v_mfma_f32_16x16x32_bf16 v[104:107], v[236:239], v[172:175], v[104:107]
	v_mfma_f32_16x16x32_bf16 v[96:99], v[228:231], v[180:183], v[96:99]
	v_mfma_f32_16x16x32_bf16 v[88:91], v[236:239], v[180:183], v[88:91]
	v_mfma_f32_16x16x32_bf16 v[80:83], v[228:231], v[188:191], v[80:83]
	v_mfma_f32_16x16x32_bf16 v[72:75], v[236:239], v[188:191], v[72:75]
	v_mfma_f32_16x16x32_bf16 v[68:71], v[228:231], v[220:223], v[68:71]
	v_mfma_f32_16x16x32_bf16 v[64:67], v[236:239], v[220:223], v[64:67]
	s_waitcnt lgkmcnt(0)
	v_mfma_f32_16x16x32_bf16 v[112:115], v[232:235], v[176:179], v[112:115]
	v_mfma_f32_16x16x32_bf16 v[104:107], v[240:243], v[176:179], v[104:107]
	v_mfma_f32_16x16x32_bf16 v[96:99], v[232:235], v[184:187], v[96:99]
	v_mfma_f32_16x16x32_bf16 v[88:91], v[240:243], v[184:187], v[88:91]
	v_mfma_f32_16x16x32_bf16 v[80:83], v[232:235], v[216:219], v[80:83]
	v_mfma_f32_16x16x32_bf16 v[72:75], v[240:243], v[216:219], v[72:75]
	v_mfma_f32_16x16x32_bf16 v[68:71], v[232:235], v[224:227], v[68:71]
	v_mfma_f32_16x16x32_bf16 v[64:67], v[240:243], v[224:227], v[64:67]
	s_setprio 0
	s_mov_b32 m0, s26
	v_lshl_add_u64 v[152:153], v[246:247], 0, s[66:67]
	s_barrier
	ds_read_b128 v[172:175], v155 offset:49152
	ds_read_b128 v[180:183], v155 offset:51200
	ds_read_b128 v[188:191], v155 offset:53248
	ds_read_b128 v[220:223], v155 offset:55296
	ds_read_b128 v[176:179], v155 offset:50176
	ds_read_b128 v[184:187], v155 offset:52224
	ds_read_b128 v[216:219], v155 offset:54272
	ds_read_b128 v[224:227], v155 offset:56320
	global_load_lds_dwordx4 v[152:153], off
	v_lshl_add_u64 v[152:153], v[248:249], 0, s[66:67]
	s_mov_b32 m0, s27
	s_nop 0
	global_load_lds_dwordx4 v[152:153], off
	s_barrier
	s_waitcnt lgkmcnt(4)
	s_setprio 1
	v_mfma_f32_16x16x32_bf16 v[60:63], v[156:159], v[172:175], v[60:63]
	v_mfma_f32_16x16x32_bf16 v[56:59], v[164:167], v[172:175], v[56:59]
	v_mfma_f32_16x16x32_bf16 v[52:55], v[156:159], v[180:183], v[52:55]
	v_mfma_f32_16x16x32_bf16 v[44:47], v[164:167], v[180:183], v[44:47]
	v_mfma_f32_16x16x32_bf16 v[36:39], v[156:159], v[188:191], v[36:39]
	v_mfma_f32_16x16x32_bf16 v[28:31], v[164:167], v[188:191], v[28:31]
	v_mfma_f32_16x16x32_bf16 v[20:23], v[156:159], v[220:223], v[20:23]
	v_mfma_f32_16x16x32_bf16 v[12:15], v[164:167], v[220:223], v[12:15]
	s_waitcnt lgkmcnt(0)
	v_mfma_f32_16x16x32_bf16 v[60:63], v[160:163], v[176:179], v[60:63]
	v_mfma_f32_16x16x32_bf16 v[56:59], v[168:171], v[176:179], v[56:59]
	v_mfma_f32_16x16x32_bf16 v[52:55], v[160:163], v[184:187], v[52:55]
	v_mfma_f32_16x16x32_bf16 v[44:47], v[168:171], v[184:187], v[44:47]
	v_mfma_f32_16x16x32_bf16 v[36:39], v[160:163], v[216:219], v[36:39]
	v_mfma_f32_16x16x32_bf16 v[28:31], v[168:171], v[216:219], v[28:31]
	v_mfma_f32_16x16x32_bf16 v[20:23], v[160:163], v[224:227], v[20:23]
	v_mfma_f32_16x16x32_bf16 v[12:15], v[168:171], v[224:227], v[12:15]
	s_setprio 0
	s_barrier
	s_add_i32 s10, s10, s19
	v_lshl_add_u64 v[152:153], v[250:251], 0, s[66:67]
	s_mov_b32 m0, s10
	s_nop 0
	global_load_lds_dwordx4 v[152:153], off
	v_lshl_add_u64 v[152:153], v[252:253], 0, s[66:67]
	s_add_i32 m0, s10, 0x2000
	s_nop 0
	global_load_lds_dwordx4 v[152:153], off
	s_waitcnt vmcnt(6)
	s_barrier
	s_setprio 1
	v_mfma_f32_16x16x32_bf16 v[48:51], v[228:231], v[172:175], v[48:51]
	v_mfma_f32_16x16x32_bf16 v[40:43], v[236:239], v[172:175], v[40:43]
	v_mfma_f32_16x16x32_bf16 v[32:35], v[228:231], v[180:183], v[32:35]
	v_mfma_f32_16x16x32_bf16 v[24:27], v[236:239], v[180:183], v[24:27]
	v_mfma_f32_16x16x32_bf16 v[16:19], v[228:231], v[188:191], v[16:19]
	v_mfma_f32_16x16x32_bf16 v[8:11], v[236:239], v[188:191], v[8:11]
	v_mfma_f32_16x16x32_bf16 v[4:7], v[228:231], v[220:223], v[4:7]
	v_mfma_f32_16x16x32_bf16 v[0:3], v[236:239], v[220:223], v[0:3]
	v_mfma_f32_16x16x32_bf16 v[48:51], v[232:235], v[176:179], v[48:51]
	v_mfma_f32_16x16x32_bf16 v[40:43], v[240:243], v[176:179], v[40:43]
	v_mfma_f32_16x16x32_bf16 v[32:35], v[232:235], v[184:187], v[32:35]
	v_mfma_f32_16x16x32_bf16 v[24:27], v[240:243], v[184:187], v[24:27]
	v_mfma_f32_16x16x32_bf16 v[16:19], v[232:235], v[216:219], v[16:19]
	v_mfma_f32_16x16x32_bf16 v[8:11], v[240:243], v[216:219], v[8:11]
	v_mfma_f32_16x16x32_bf16 v[4:7], v[232:235], v[224:227], v[4:7]
	v_mfma_f32_16x16x32_bf16 v[0:3], v[240:243], v[224:227], v[0:3]
	s_setprio 0
	s_add_u32 s8, s8, 0x100
	s_addc_u32 s9, s9, 0
	s_add_u32 s38, s38, 0x100
	s_addc_u32 s39, s39, 0
	s_cmp_ge_u32 s40, s28
	s_mov_b32 s10, s40
	s_barrier
	s_cbranch_scc0 .LBB0_1234
	v_mov_b32_e32 v152, v135
	s_mov_b64 s[8:9], s[0:1]
	v_readfirstlane_b32 s10, v152
	s_ashr_i32 s12, s10, 2
	s_load_dwordx2 s[8:9], s[8:9], 0x88
	s_lshl_b32 s11, s36, 8
	s_andn2_b32 s12, s12, 63
	s_lshr_b32 s10, s10, 1
	s_add_i32 s12, s12, s11
	s_lshl_b32 s11, s37, 8
	s_and_b32 s10, s10, 0x60
	v_and_or_b32 v156, v152, 15, s12
	s_or_b32 s10, s10, s11
	v_lshrrev_b32_e32 v152, 1, v152
	v_and_or_b32 v152, v152, 24, s10
	v_ashrrev_i32_e32 v153, 31, v152
	s_waitcnt lgkmcnt(0)
	v_lshl_add_u64 v[152:153], v[152:153], 1, s[8:9]
	s_mov_b64 s[8:9], 0x62a4400
	v_ashrrev_i32_e32 v157, 31, v156
	v_lshl_add_u64 v[158:159], v[152:153], 0, s[8:9]
	v_lshlrev_b64 v[152:153], 11, v[156:157]
	v_lshl_add_u64 v[152:153], v[158:159], 0, v[152:153]
	s_mov_b64 s[8:9], 0x40000
	v_cvt_pk_bf16_f32 v68, v68, v69
	v_cvt_pk_bf16_f32 v69, v70, v71
	v_cvt_pk_bf16_f32 v70, v64, v65
	v_lshl_add_u64 v[64:65], v[152:153], 0, s[8:9]
	s_mov_b32 s8, 0x40000
	v_cvt_pk_bf16_f32 v60, v60, v61
	v_cvt_pk_bf16_f32 v61, v62, v63
	v_cvt_pk_bf16_f32 v62, v56, v57
	v_add_co_u32_e32 v56, vcc, s8, v152
	v_cvt_pk_bf16_f32 v48, v48, v49
	v_cvt_pk_bf16_f32 v49, v50, v51
	s_mov_b64 s[8:9], 0x48000
	s_nop 0
	v_addc_co_u32_e32 v57, vcc, 0, v153, vcc
	v_cvt_pk_bf16_f32 v50, v40, v41
	v_cvt_pk_bf16_f32 v51, v42, v43
	global_store_dwordx4 v[64:65], v[48:51], off offset:256 sc1
	v_cvt_pk_bf16_f32 v42, v44, v45
	v_cvt_pk_bf16_f32 v32, v32, v33
	v_cvt_pk_bf16_f32 v33, v34, v35
	v_cvt_pk_bf16_f32 v112, v112, v113
	v_cvt_pk_bf16_f32 v113, v114, v115
	s_nop 1
	v_lshl_add_u64 v[48:49], v[152:153], 0, s[8:9]
	s_mov_b32 s8, 0x48000
	v_add_co_u32_e32 v44, vcc, s8, v152
	s_mov_b64 s[8:9], 0x50000
	v_cvt_pk_bf16_f32 v114, v104, v105
	v_or_b32_e32 v104, 16, v156
	v_addc_co_u32_e32 v45, vcc, 0, v153, vcc
	v_cvt_pk_bf16_f32 v34, v24, v25
	v_cvt_pk_bf16_f32 v35, v26, v27
	global_store_dwordx4 v[48:49], v[32:35], off offset:256 sc1
	v_ashrrev_i32_e32 v105, 31, v104
	v_cvt_pk_bf16_f32 v96, v96, v97
	v_cvt_pk_bf16_f32 v97, v98, v99
	v_cvt_pk_bf16_f32 v98, v88, v89
	v_or_b32_e32 v88, 32, v156
	v_lshl_add_u64 v[32:33], v[152:153], 0, s[8:9]
	s_mov_b32 s8, 0x50000
	v_cvt_pk_bf16_f32 v26, v28, v29
	v_add_co_u32_e32 v28, vcc, s8, v152
	v_cvt_pk_bf16_f32 v16, v16, v17
	v_cvt_pk_bf16_f32 v17, v18, v19
	s_mov_b64 s[8:9], 0x58000
	v_lshlrev_b64 v[104:105], 11, v[104:105]
	v_ashrrev_i32_e32 v89, 31, v88
	v_cvt_pk_bf16_f32 v80, v80, v81
	v_cvt_pk_bf16_f32 v81, v82, v83
	v_cvt_pk_bf16_f32 v82, v72, v73
	v_or_b32_e32 v72, 48, v156
	v_addc_co_u32_e32 v29, vcc, 0, v153, vcc
	v_cvt_pk_bf16_f32 v18, v8, v9
	v_cvt_pk_bf16_f32 v19, v10, v11
	global_store_dwordx4 v[32:33], v[16:19], off offset:256 sc1
	v_cvt_pk_bf16_f32 v115, v106, v107
	global_store_dwordx4 v[152:153], v[112:115], off offset:256 sc1
	v_lshlrev_b64 v[88:89], 11, v[88:89]
	v_lshl_add_u64 v[16:17], v[152:153], 0, s[8:9]
	s_mov_b32 s8, 0x58000
	v_lshl_add_u64 v[112:113], v[158:159], 0, v[104:105]
	v_ashrrev_i32_e32 v73, 31, v72
	v_cvt_pk_bf16_f32 v10, v12, v13
	v_add_co_u32_e32 v12, vcc, s8, v152
	v_cvt_pk_bf16_f32 v99, v90, v91
	global_store_dwordx4 v[112:113], v[96:99], off offset:256 sc1
	v_lshlrev_b64 v[72:73], 11, v[72:73]
	v_addc_co_u32_e32 v13, vcc, 0, v153, vcc
	v_lshl_add_u64 v[96:97], v[158:159], 0, v[88:89]
	v_cvt_pk_bf16_f32 v83, v74, v75
	global_store_dwordx4 v[96:97], v[80:83], off offset:256 sc1
	s_and_b64 vcc, exec, s[4:5]
	s_mov_b32 s37, s34
	v_lshl_add_u64 v[80:81], v[158:159], 0, v[72:73]
	s_mov_b32 s36, s35
	s_mov_b64 s[10:11], s[6:7]
	s_mov_b64 s[12:13], s[2:3]
	v_cvt_pk_bf16_f32 v124, v124, v125
	v_cvt_pk_bf16_f32 v125, v126, v127
	v_cvt_pk_bf16_f32 v126, v120, v121
	v_cvt_pk_bf16_f32 v127, v122, v123
	global_store_dwordx4 v[152:153], v[124:127], off sc1
	v_cvt_pk_bf16_f32 v104, v116, v117
	v_cvt_pk_bf16_f32 v105, v118, v119
	v_cvt_pk_bf16_f32 v106, v108, v109
	v_cvt_pk_bf16_f32 v107, v110, v111
	global_store_dwordx4 v[112:113], v[104:107], off sc1
	v_cvt_pk_bf16_f32 v88, v100, v101
	v_cvt_pk_bf16_f32 v89, v102, v103
	v_cvt_pk_bf16_f32 v90, v92, v93
	v_cvt_pk_bf16_f32 v91, v94, v95
	global_store_dwordx4 v[96:97], v[88:91], off sc1
	v_cvt_pk_bf16_f32 v72, v84, v85
	v_cvt_pk_bf16_f32 v73, v86, v87
	v_cvt_pk_bf16_f32 v74, v76, v77
	v_cvt_pk_bf16_f32 v75, v78, v79
	global_store_dwordx4 v[80:81], v[72:75], off sc1
	v_cvt_pk_bf16_f32 v71, v66, v67
	global_store_dwordx4 v[80:81], v[68:71], off offset:256 sc1
	v_cvt_pk_bf16_f32 v63, v58, v59
	global_store_dwordx4 v[56:57], v[60:63], off sc1
	v_cvt_pk_bf16_f32 v40, v52, v53
	v_cvt_pk_bf16_f32 v41, v54, v55
	v_cvt_pk_bf16_f32 v43, v46, v47
	global_store_dwordx4 v[44:45], v[40:43], off sc1
	v_cvt_pk_bf16_f32 v24, v36, v37
	v_cvt_pk_bf16_f32 v25, v38, v39
	v_cvt_pk_bf16_f32 v27, v30, v31
	global_store_dwordx4 v[28:29], v[24:27], off sc1
	v_cvt_pk_bf16_f32 v8, v20, v21
	v_cvt_pk_bf16_f32 v9, v22, v23
	v_cvt_pk_bf16_f32 v11, v14, v15
	global_store_dwordx4 v[12:13], v[8:11], off sc1
	v_cvt_pk_bf16_f32 v4, v4, v5
	v_cvt_pk_bf16_f32 v5, v6, v7
	v_cvt_pk_bf16_f32 v6, v0, v1
	v_cvt_pk_bf16_f32 v7, v2, v3
	global_store_dwordx4 v[16:17], v[4:7], off offset:256 sc1
	s_cbranch_vccz .LBB0_1223
	s_waitcnt vmcnt(0)
	s_cmpk_gt_u32 s14, 0xff
	s_cbranch_scc1 .LBB0_1238
	s_barrier
